# v22 + loop-edge edit: each GEMM K-loop's counter/pointer updates and exit compare moved from after the last barrier into the MFMA shadow of the last compute segment
# speedup vs baseline: 1.0053x; 1.0053x over previous
.LBB0_166:
	ds_read_b128 v[128:131], v189
	ds_read_b128 v[132:135], v189 offset:1024
	ds_read_b128 v[136:139], v189 offset:2048
	ds_read_b128 v[140:143], v189 offset:3072
	ds_read_b128 v[166:169], v189 offset:16384
	ds_read_b128 v[170:173], v189 offset:17408
	ds_read_b128 v[174:177], v189 offset:18432
	ds_read_b128 v[192:195], v189 offset:19456
	s_add_u32 s23, s26, 0xfffc0080
	s_addc_u32 s28, s27, -1
	s_cmp_eq_u32 s53, 12
	s_cselect_b32 s31, s7, s28
	s_cselect_b32 s30, s19, s23
	s_cselect_b32 s29, s17, s52
	s_cselect_b32 s28, s50, s51
	s_add_i32 m0, s15, 0xc000
	ds_read_b128 v[196:199], v190
	ds_read_b128 v[200:203], v190 offset:1024
	ds_read_b128 v[204:207], v190 offset:2048
	ds_read_b128 v[208:211], v190 offset:3072
	ds_read_b128 v[212:215], v190 offset:4096
	ds_read_b128 v[216:219], v190 offset:5120
	ds_read_b128 v[220:223], v190 offset:6144
	ds_read_b128 v[224:227], v190 offset:7168
	global_load_lds_dwordx4 v144, s[26:27]
	s_add_i32 m0, s15, 0xe000
	v_mov_b32_e32 v149, v145
	global_load_lds_dwordx4 v148, s[26:27]
	s_waitcnt vmcnt(8)
	s_waitcnt lgkmcnt(0)
	s_barrier
	s_setprio 1
	s_waitcnt lgkmcnt(0)
	v_mfma_f32_16x16x32_bf16 v[124:127], v[128:131], v[196:199], v[124:127]
	v_mfma_f32_16x16x32_bf16 v[120:123], v[136:139], v[196:199], v[120:123]
	v_mfma_f32_16x16x32_bf16 v[116:119], v[128:131], v[204:207], v[116:119]
	v_mfma_f32_16x16x32_bf16 v[112:115], v[136:139], v[204:207], v[112:115]
	v_mfma_f32_16x16x32_bf16 v[100:103], v[128:131], v[212:215], v[100:103]
	v_mfma_f32_16x16x32_bf16 v[96:99], v[136:139], v[212:215], v[96:99]
	v_mfma_f32_16x16x32_bf16 v[84:87], v[128:131], v[220:223], v[84:87]
	v_mfma_f32_16x16x32_bf16 v[80:83], v[136:139], v[220:223], v[80:83]
	v_mfma_f32_16x16x32_bf16 v[124:127], v[132:135], v[200:203], v[124:127]
	v_mfma_f32_16x16x32_bf16 v[120:123], v[140:143], v[200:203], v[120:123]
	v_mfma_f32_16x16x32_bf16 v[116:119], v[132:135], v[208:211], v[116:119]
	v_mfma_f32_16x16x32_bf16 v[112:115], v[140:143], v[208:211], v[112:115]
	v_mfma_f32_16x16x32_bf16 v[100:103], v[132:135], v[216:219], v[100:103]
	v_mfma_f32_16x16x32_bf16 v[96:99], v[140:143], v[216:219], v[96:99]
	v_mfma_f32_16x16x32_bf16 v[84:87], v[132:135], v[224:227], v[84:87]
	v_mfma_f32_16x16x32_bf16 v[80:83], v[140:143], v[224:227], v[80:83]
	s_setprio 0
	s_setprio 1
	v_mfma_f32_16x16x32_bf16 v[108:111], v[166:169], v[196:199], v[108:111]
	v_mfma_f32_16x16x32_bf16 v[104:107], v[174:177], v[196:199], v[104:107]
	v_mfma_f32_16x16x32_bf16 v[92:95], v[166:169], v[204:207], v[92:95]
	v_mfma_f32_16x16x32_bf16 v[88:91], v[174:177], v[204:207], v[88:91]
	v_mfma_f32_16x16x32_bf16 v[76:79], v[166:169], v[212:215], v[76:79]
	v_mfma_f32_16x16x32_bf16 v[72:75], v[174:177], v[212:215], v[72:75]
	v_mfma_f32_16x16x32_bf16 v[68:71], v[166:169], v[220:223], v[68:71]
	v_mfma_f32_16x16x32_bf16 v[64:67], v[174:177], v[220:223], v[64:67]
	v_mfma_f32_16x16x32_bf16 v[108:111], v[170:173], v[200:203], v[108:111]
	v_mfma_f32_16x16x32_bf16 v[104:107], v[192:195], v[200:203], v[104:107]
	v_mfma_f32_16x16x32_bf16 v[92:95], v[170:173], v[208:211], v[92:95]
	v_mfma_f32_16x16x32_bf16 v[88:91], v[192:195], v[208:211], v[88:91]
	v_mfma_f32_16x16x32_bf16 v[76:79], v[170:173], v[216:219], v[76:79]
	v_mfma_f32_16x16x32_bf16 v[72:75], v[192:195], v[216:219], v[72:75]
	v_mfma_f32_16x16x32_bf16 v[68:71], v[170:173], v[224:227], v[68:71]
	v_mfma_f32_16x16x32_bf16 v[64:67], v[192:195], v[224:227], v[64:67]
	s_setprio 0
	s_barrier
	s_mov_b32 m0, s34
	ds_read_b128 v[196:199], v190 offset:16384
	ds_read_b128 v[200:203], v190 offset:17408
	ds_read_b128 v[204:207], v190 offset:18432
	ds_read_b128 v[208:211], v190 offset:19456
	ds_read_b128 v[212:215], v190 offset:20480
	ds_read_b128 v[216:219], v190 offset:21504
	ds_read_b128 v[220:223], v190 offset:22528
	ds_read_b128 v[224:227], v190 offset:23552
	global_load_lds_dwordx4 v146, s[28:29]
	s_mov_b32 m0, s35
	s_add_u32 s54, s28, 0x40000
	global_load_lds_dwordx4 v150, s[28:29]
	s_addc_u32 s55, s29, 0
	s_mov_b32 m0, s36
	v_mov_b32_e32 v147, v145
	global_load_lds_dwordx4 v146, s[54:55]
	s_mov_b32 m0, s37
	v_mov_b32_e32 v151, v145
	global_load_lds_dwordx4 v150, s[54:55]
	s_waitcnt vmcnt(6)
	s_waitcnt lgkmcnt(0)
	s_barrier
	s_setprio 1
	s_waitcnt lgkmcnt(0)
	v_mfma_f32_16x16x32_bf16 v[60:63], v[128:131], v[196:199], v[60:63]
	v_mfma_f32_16x16x32_bf16 v[56:59], v[136:139], v[196:199], v[56:59]
	s_mov_b32 m0, s15
	v_lshl_add_u64 v[180:181], s[28:29], 0, v[146:147]
	v_mfma_f32_16x16x32_bf16 v[52:55], v[128:131], v[204:207], v[52:55]
	global_load_lds_dwordx4 v144, s[30:31]
	v_mfma_f32_16x16x32_bf16 v[48:51], v[136:139], v[204:207], v[48:51]
	v_mfma_f32_16x16x32_bf16 v[36:39], v[128:131], v[212:215], v[36:39]
	v_mfma_f32_16x16x32_bf16 v[32:35], v[136:139], v[212:215], v[32:35]
	v_mfma_f32_16x16x32_bf16 v[20:23], v[128:131], v[220:223], v[20:23]
	v_mfma_f32_16x16x32_bf16 v[16:19], v[136:139], v[220:223], v[16:19]
	v_mfma_f32_16x16x32_bf16 v[60:63], v[132:135], v[200:203], v[60:63]
	v_mfma_f32_16x16x32_bf16 v[56:59], v[140:143], v[200:203], v[56:59]
	v_mfma_f32_16x16x32_bf16 v[52:55], v[132:135], v[208:211], v[52:55]
	v_mfma_f32_16x16x32_bf16 v[48:51], v[140:143], v[208:211], v[48:51]
	v_mfma_f32_16x16x32_bf16 v[36:39], v[132:135], v[216:219], v[36:39]
	v_mfma_f32_16x16x32_bf16 v[32:35], v[140:143], v[216:219], v[32:35]
	v_mfma_f32_16x16x32_bf16 v[20:23], v[132:135], v[224:227], v[20:23]
	v_mfma_f32_16x16x32_bf16 v[16:19], v[140:143], v[224:227], v[16:19]
	s_mov_b32 m0, s38
	v_lshl_add_u64 v[228:229], s[28:29], 0, v[150:151]
	s_setprio 0
	s_setprio 1
	v_mfma_f32_16x16x32_bf16 v[44:47], v[166:169], v[196:199], v[44:47]
	global_load_lds_dwordx4 v148, s[30:31]
	v_lshl_add_u64 v[230:231], s[30:31], 0, v[144:145]
	v_lshl_add_u64 v[232:233], s[30:31], 0, v[148:149]
	v_mfma_f32_16x16x32_bf16 v[40:43], v[174:177], v[196:199], v[40:43]
	v_mfma_f32_16x16x32_bf16 v[28:31], v[166:169], v[204:207], v[28:31]
	v_mfma_f32_16x16x32_bf16 v[24:27], v[174:177], v[204:207], v[24:27]
	v_mfma_f32_16x16x32_bf16 v[12:15], v[166:169], v[212:215], v[12:15]
	v_mfma_f32_16x16x32_bf16 v[8:11], v[174:177], v[212:215], v[8:11]
	v_mfma_f32_16x16x32_bf16 v[4:7], v[166:169], v[220:223], v[4:7]
	v_mfma_f32_16x16x32_bf16 v[0:3], v[174:177], v[220:223], v[0:3]
	v_mfma_f32_16x16x32_bf16 v[44:47], v[170:173], v[200:203], v[44:47]
	v_mfma_f32_16x16x32_bf16 v[40:43], v[192:195], v[200:203], v[40:43]
	v_mfma_f32_16x16x32_bf16 v[28:31], v[170:173], v[208:211], v[28:31]
	v_mfma_f32_16x16x32_bf16 v[24:27], v[192:195], v[208:211], v[24:27]
	v_mfma_f32_16x16x32_bf16 v[12:15], v[170:173], v[216:219], v[12:15]
	v_mfma_f32_16x16x32_bf16 v[8:11], v[192:195], v[216:219], v[8:11]
	v_mfma_f32_16x16x32_bf16 v[4:7], v[170:173], v[224:227], v[4:7]
	v_mfma_f32_16x16x32_bf16 v[0:3], v[192:195], v[224:227], v[0:3]
	s_setprio 0
	s_barrier
	ds_read_b128 v[128:131], v189 offset:32768
	ds_read_b128 v[132:135], v189 offset:33792
	ds_read_b128 v[136:139], v189 offset:34816
	ds_read_b128 v[140:143], v189 offset:35840
	ds_read_b128 v[166:169], v189 offset:49152
	ds_read_b128 v[170:173], v189 offset:50176
	ds_read_b128 v[174:177], v189 offset:51200
	ds_read_b128 v[192:195], v189 offset:52224
	s_add_u32 s30, s30, 0x40000
	s_addc_u32 s31, s31, 0
	s_mov_b32 m0, s39
	ds_read_b128 v[196:199], v190 offset:32768
	ds_read_b128 v[200:203], v190 offset:33792
	ds_read_b128 v[204:207], v190 offset:34816
	ds_read_b128 v[208:211], v190 offset:35840
	ds_read_b128 v[212:215], v190 offset:36864
	ds_read_b128 v[216:219], v190 offset:37888
	ds_read_b128 v[220:223], v190 offset:38912
	ds_read_b128 v[224:227], v190 offset:39936
	global_load_lds_dwordx4 v144, s[30:31]
	s_mov_b32 m0, s40
	s_nop 0
	global_load_lds_dwordx4 v148, s[30:31]
	s_waitcnt vmcnt(8)
	s_waitcnt lgkmcnt(0)
	s_barrier
	s_setprio 1
	s_waitcnt lgkmcnt(0)
	v_mfma_f32_16x16x32_bf16 v[124:127], v[128:131], v[196:199], v[124:127]
	v_mfma_f32_16x16x32_bf16 v[120:123], v[136:139], v[196:199], v[120:123]
	v_mfma_f32_16x16x32_bf16 v[116:119], v[128:131], v[204:207], v[116:119]
	v_mfma_f32_16x16x32_bf16 v[112:115], v[136:139], v[204:207], v[112:115]
	v_mfma_f32_16x16x32_bf16 v[100:103], v[128:131], v[212:215], v[100:103]
	v_mfma_f32_16x16x32_bf16 v[96:99], v[136:139], v[212:215], v[96:99]
	v_mfma_f32_16x16x32_bf16 v[84:87], v[128:131], v[220:223], v[84:87]
	v_mfma_f32_16x16x32_bf16 v[80:83], v[136:139], v[220:223], v[80:83]
	v_mfma_f32_16x16x32_bf16 v[124:127], v[132:135], v[200:203], v[124:127]
	v_mfma_f32_16x16x32_bf16 v[120:123], v[140:143], v[200:203], v[120:123]
	v_mfma_f32_16x16x32_bf16 v[116:119], v[132:135], v[208:211], v[116:119]
	v_mfma_f32_16x16x32_bf16 v[112:115], v[140:143], v[208:211], v[112:115]
	v_mfma_f32_16x16x32_bf16 v[100:103], v[132:135], v[216:219], v[100:103]
	v_mfma_f32_16x16x32_bf16 v[96:99], v[140:143], v[216:219], v[96:99]
	v_mfma_f32_16x16x32_bf16 v[84:87], v[132:135], v[224:227], v[84:87]
	v_mfma_f32_16x16x32_bf16 v[80:83], v[140:143], v[224:227], v[80:83]
	s_setprio 0
	s_setprio 1
	v_mfma_f32_16x16x32_bf16 v[108:111], v[166:169], v[196:199], v[108:111]
	v_mfma_f32_16x16x32_bf16 v[104:107], v[174:177], v[196:199], v[104:107]
	v_mfma_f32_16x16x32_bf16 v[92:95], v[166:169], v[204:207], v[92:95]
	v_mfma_f32_16x16x32_bf16 v[88:91], v[174:177], v[204:207], v[88:91]
	v_mfma_f32_16x16x32_bf16 v[76:79], v[166:169], v[212:215], v[76:79]
	v_mfma_f32_16x16x32_bf16 v[72:75], v[174:177], v[212:215], v[72:75]
	v_mfma_f32_16x16x32_bf16 v[68:71], v[166:169], v[220:223], v[68:71]
	v_mfma_f32_16x16x32_bf16 v[64:67], v[174:177], v[220:223], v[64:67]
	v_mfma_f32_16x16x32_bf16 v[108:111], v[170:173], v[200:203], v[108:111]
	v_mfma_f32_16x16x32_bf16 v[104:107], v[192:195], v[200:203], v[104:107]
	v_mfma_f32_16x16x32_bf16 v[92:95], v[170:173], v[208:211], v[92:95]
	v_mfma_f32_16x16x32_bf16 v[88:91], v[192:195], v[208:211], v[88:91]
	v_mfma_f32_16x16x32_bf16 v[76:79], v[170:173], v[216:219], v[76:79]
	v_mfma_f32_16x16x32_bf16 v[72:75], v[192:195], v[216:219], v[72:75]
	v_mfma_f32_16x16x32_bf16 v[68:71], v[170:173], v[224:227], v[68:71]
	v_mfma_f32_16x16x32_bf16 v[64:67], v[192:195], v[224:227], v[64:67]
	s_setprio 0
	s_barrier
	s_mov_b32 m0, s42
	v_lshl_add_u64 v[180:181], v[180:181], 0, s[10:11]
	ds_read_b128 v[196:199], v190 offset:49152
	ds_read_b128 v[200:203], v190 offset:50176
	ds_read_b128 v[204:207], v190 offset:51200
	ds_read_b128 v[208:211], v190 offset:52224
	ds_read_b128 v[212:215], v190 offset:53248
	ds_read_b128 v[216:219], v190 offset:54272
	ds_read_b128 v[220:223], v190 offset:55296
	ds_read_b128 v[224:227], v190 offset:56320
	global_load_lds_dwordx4 v[180:181], off
	v_lshl_add_u64 v[180:181], v[228:229], 0, s[10:11]
	s_mov_b32 m0, s43
	s_add_u32 s28, s28, 0x40080
	global_load_lds_dwordx4 v[180:181], off
	s_addc_u32 s29, s29, 0
	s_mov_b32 m0, s48
	v_lshl_add_u64 v[180:181], v[230:231], 0, s[10:11]
	global_load_lds_dwordx4 v146, s[28:29]
	s_mov_b32 m0, s49
	s_nop 0
	global_load_lds_dwordx4 v150, s[28:29]
	s_waitcnt vmcnt(6)
	s_waitcnt lgkmcnt(0)
	s_barrier
	s_setprio 1
	s_waitcnt lgkmcnt(0)
	v_mfma_f32_16x16x32_bf16 v[60:63], v[128:131], v[196:199], v[60:63]
	v_mfma_f32_16x16x32_bf16 v[56:59], v[136:139], v[196:199], v[56:59]
	s_mov_b32 m0, s44
	v_mfma_f32_16x16x32_bf16 v[52:55], v[128:131], v[204:207], v[52:55]
	global_load_lds_dwordx4 v[180:181], off
	v_mfma_f32_16x16x32_bf16 v[48:51], v[136:139], v[204:207], v[48:51]
	v_mfma_f32_16x16x32_bf16 v[36:39], v[128:131], v[212:215], v[36:39]
	v_mfma_f32_16x16x32_bf16 v[32:35], v[136:139], v[212:215], v[32:35]
	v_mfma_f32_16x16x32_bf16 v[20:23], v[128:131], v[220:223], v[20:23]
	v_mfma_f32_16x16x32_bf16 v[16:19], v[136:139], v[220:223], v[16:19]
	v_mfma_f32_16x16x32_bf16 v[60:63], v[132:135], v[200:203], v[60:63]
	v_mfma_f32_16x16x32_bf16 v[56:59], v[140:143], v[200:203], v[56:59]
	v_mfma_f32_16x16x32_bf16 v[52:55], v[132:135], v[208:211], v[52:55]
	v_mfma_f32_16x16x32_bf16 v[48:51], v[140:143], v[208:211], v[48:51]
	v_mfma_f32_16x16x32_bf16 v[36:39], v[132:135], v[216:219], v[36:39]
	v_mfma_f32_16x16x32_bf16 v[32:35], v[140:143], v[216:219], v[32:35]
	v_mfma_f32_16x16x32_bf16 v[20:23], v[132:135], v[224:227], v[20:23]
	v_mfma_f32_16x16x32_bf16 v[16:19], v[140:143], v[224:227], v[16:19]
	v_lshl_add_u64 v[180:181], v[232:233], 0, s[10:11]
	s_mov_b32 m0, s45
	s_setprio 0
	s_setprio 1
	v_mfma_f32_16x16x32_bf16 v[44:47], v[166:169], v[196:199], v[44:47]
	global_load_lds_dwordx4 v[180:181], off
	v_mfma_f32_16x16x32_bf16 v[40:43], v[174:177], v[196:199], v[40:43]
	v_mfma_f32_16x16x32_bf16 v[28:31], v[166:169], v[204:207], v[28:31]
	v_mfma_f32_16x16x32_bf16 v[24:27], v[174:177], v[204:207], v[24:27]
	v_mfma_f32_16x16x32_bf16 v[12:15], v[166:169], v[212:215], v[12:15]
	v_mfma_f32_16x16x32_bf16 v[8:11], v[174:177], v[212:215], v[8:11]
	v_mfma_f32_16x16x32_bf16 v[4:7], v[166:169], v[220:223], v[4:7]
	v_mfma_f32_16x16x32_bf16 v[0:3], v[174:177], v[220:223], v[0:3]
	v_mfma_f32_16x16x32_bf16 v[44:47], v[170:173], v[200:203], v[44:47]
	s_add_i32 s53, s53, 2
	v_mfma_f32_16x16x32_bf16 v[40:43], v[192:195], v[200:203], v[40:43]
	s_add_u32 s26, s26, 0x100
	v_mfma_f32_16x16x32_bf16 v[28:31], v[170:173], v[208:211], v[28:31]
	s_addc_u32 s27, s27, 0
	v_mfma_f32_16x16x32_bf16 v[24:27], v[192:195], v[208:211], v[24:27]
	s_add_u32 s51, s51, 0x100
	v_mfma_f32_16x16x32_bf16 v[12:15], v[170:173], v[216:219], v[12:15]
	s_addc_u32 s52, s52, 0
	v_mfma_f32_16x16x32_bf16 v[8:11], v[192:195], v[216:219], v[8:11]
	s_cmp_gt_u32 s53, 13
	v_mfma_f32_16x16x32_bf16 v[4:7], v[170:173], v[224:227], v[4:7]
	v_mfma_f32_16x16x32_bf16 v[0:3], v[192:195], v[224:227], v[0:3]
	s_setprio 0
	s_barrier
	s_cbranch_scc0 .LBB0_166
	s_and_b64 vcc, exec, s[12:13]
	s_cbranch_vccz .LBB0_169
	s_barrier

.LBB0_206:
	ds_read_b128 v[144:147], v142
	ds_read_b128 v[148:151], v142 offset:1024
	ds_read_b128 v[152:155], v142 offset:2048
	ds_read_b128 v[156:159], v142 offset:3072
	ds_read_b128 v[164:167], v142 offset:16384
	ds_read_b128 v[168:171], v142 offset:17408
	ds_read_b128 v[172:175], v142 offset:18432
	ds_read_b128 v[176:179], v142 offset:19456
	s_add_u32 s23, s26, 0xfffc0080
	s_addc_u32 s28, s27, -1
	s_cmp_eq_u32 s53, 12
	s_cselect_b32 s31, s15, s28
	s_cselect_b32 s30, s49, s23
	s_cselect_b32 s29, s13, s52
	s_cselect_b32 s28, s50, s51
	s_add_i32 m0, s3, 0xc000
	ds_read_b128 v[180:183], v143
	ds_read_b128 v[186:189], v143 offset:1024
	ds_read_b128 v[190:193], v143 offset:2048
	ds_read_b128 v[194:197], v143 offset:3072
	ds_read_b128 v[198:201], v143 offset:4096
	ds_read_b128 v[202:205], v143 offset:5120
	ds_read_b128 v[206:209], v143 offset:6144
	ds_read_b128 v[210:213], v143 offset:7168
	global_load_lds_dwordx4 v128, s[26:27]
	s_add_i32 m0, s3, 0xe000
	v_mov_b32_e32 v131, v129
	global_load_lds_dwordx4 v130, s[26:27]
	s_waitcnt vmcnt(8)
	s_waitcnt lgkmcnt(0)
	s_barrier
	s_setprio 1
	s_waitcnt lgkmcnt(0)
	v_mfma_f32_16x16x32_bf16 v[124:127], v[144:147], v[180:183], v[124:127]
	v_mfma_f32_16x16x32_bf16 v[120:123], v[152:155], v[180:183], v[120:123]
	v_mfma_f32_16x16x32_bf16 v[116:119], v[144:147], v[190:193], v[116:119]
	v_mfma_f32_16x16x32_bf16 v[112:115], v[152:155], v[190:193], v[112:115]
	v_mfma_f32_16x16x32_bf16 v[100:103], v[144:147], v[198:201], v[100:103]
	v_mfma_f32_16x16x32_bf16 v[96:99], v[152:155], v[198:201], v[96:99]
	v_mfma_f32_16x16x32_bf16 v[84:87], v[144:147], v[206:209], v[84:87]
	v_mfma_f32_16x16x32_bf16 v[80:83], v[152:155], v[206:209], v[80:83]
	v_mfma_f32_16x16x32_bf16 v[124:127], v[148:151], v[186:189], v[124:127]
	v_mfma_f32_16x16x32_bf16 v[120:123], v[156:159], v[186:189], v[120:123]
	v_mfma_f32_16x16x32_bf16 v[116:119], v[148:151], v[194:197], v[116:119]
	v_mfma_f32_16x16x32_bf16 v[112:115], v[156:159], v[194:197], v[112:115]
	v_mfma_f32_16x16x32_bf16 v[100:103], v[148:151], v[202:205], v[100:103]
	v_mfma_f32_16x16x32_bf16 v[96:99], v[156:159], v[202:205], v[96:99]
	v_mfma_f32_16x16x32_bf16 v[84:87], v[148:151], v[210:213], v[84:87]
	v_mfma_f32_16x16x32_bf16 v[80:83], v[156:159], v[210:213], v[80:83]
	s_setprio 0
	s_setprio 1
	v_mfma_f32_16x16x32_bf16 v[108:111], v[164:167], v[180:183], v[108:111]
	v_mfma_f32_16x16x32_bf16 v[104:107], v[172:175], v[180:183], v[104:107]
	v_mfma_f32_16x16x32_bf16 v[92:95], v[164:167], v[190:193], v[92:95]
	v_mfma_f32_16x16x32_bf16 v[88:91], v[172:175], v[190:193], v[88:91]
	v_mfma_f32_16x16x32_bf16 v[76:79], v[164:167], v[198:201], v[76:79]
	v_mfma_f32_16x16x32_bf16 v[72:75], v[172:175], v[198:201], v[72:75]
	v_mfma_f32_16x16x32_bf16 v[68:71], v[164:167], v[206:209], v[68:71]
	v_mfma_f32_16x16x32_bf16 v[64:67], v[172:175], v[206:209], v[64:67]
	v_mfma_f32_16x16x32_bf16 v[108:111], v[168:171], v[186:189], v[108:111]
	v_mfma_f32_16x16x32_bf16 v[104:107], v[176:179], v[186:189], v[104:107]
	v_mfma_f32_16x16x32_bf16 v[92:95], v[168:171], v[194:197], v[92:95]
	v_mfma_f32_16x16x32_bf16 v[88:91], v[176:179], v[194:197], v[88:91]
	v_mfma_f32_16x16x32_bf16 v[76:79], v[168:171], v[202:205], v[76:79]
	v_mfma_f32_16x16x32_bf16 v[72:75], v[176:179], v[202:205], v[72:75]
	v_mfma_f32_16x16x32_bf16 v[68:71], v[168:171], v[210:213], v[68:71]
	v_mfma_f32_16x16x32_bf16 v[64:67], v[176:179], v[210:213], v[64:67]
	s_setprio 0
	s_barrier
	s_mov_b32 m0, s17
	ds_read_b128 v[180:183], v143 offset:16384
	ds_read_b128 v[186:189], v143 offset:17408
	ds_read_b128 v[190:193], v143 offset:18432
	ds_read_b128 v[194:197], v143 offset:19456
	ds_read_b128 v[198:201], v143 offset:20480
	ds_read_b128 v[202:205], v143 offset:21504
	ds_read_b128 v[206:209], v143 offset:22528
	ds_read_b128 v[210:213], v143 offset:23552
	global_load_lds_dwordx4 v138, s[28:29]
	s_mov_b32 m0, s22
	s_add_u32 s54, s28, 0x40000
	global_load_lds_dwordx4 v132, s[28:29]
	s_addc_u32 s55, s29, 0
	s_mov_b32 m0, s34
	v_mov_b32_e32 v139, v129
	global_load_lds_dwordx4 v138, s[54:55]
	s_mov_b32 m0, s35
	v_mov_b32_e32 v133, v129
	global_load_lds_dwordx4 v132, s[54:55]
	s_waitcnt vmcnt(6)
	s_waitcnt lgkmcnt(0)
	s_barrier
	s_setprio 1
	s_waitcnt lgkmcnt(0)
	v_mfma_f32_16x16x32_bf16 v[60:63], v[144:147], v[180:183], v[60:63]
	v_mfma_f32_16x16x32_bf16 v[56:59], v[152:155], v[180:183], v[56:59]
	s_mov_b32 m0, s3
	v_lshl_add_u64 v[214:215], s[28:29], 0, v[138:139]
	v_mfma_f32_16x16x32_bf16 v[52:55], v[144:147], v[190:193], v[52:55]
	global_load_lds_dwordx4 v128, s[30:31]
	v_mfma_f32_16x16x32_bf16 v[48:51], v[152:155], v[190:193], v[48:51]
	v_mfma_f32_16x16x32_bf16 v[36:39], v[144:147], v[198:201], v[36:39]
	v_mfma_f32_16x16x32_bf16 v[32:35], v[152:155], v[198:201], v[32:35]
	v_mfma_f32_16x16x32_bf16 v[20:23], v[144:147], v[206:209], v[20:23]
	v_mfma_f32_16x16x32_bf16 v[16:19], v[152:155], v[206:209], v[16:19]
	v_mfma_f32_16x16x32_bf16 v[60:63], v[148:151], v[186:189], v[60:63]
	v_mfma_f32_16x16x32_bf16 v[56:59], v[156:159], v[186:189], v[56:59]
	v_mfma_f32_16x16x32_bf16 v[52:55], v[148:151], v[194:197], v[52:55]
	v_mfma_f32_16x16x32_bf16 v[48:51], v[156:159], v[194:197], v[48:51]
	v_mfma_f32_16x16x32_bf16 v[36:39], v[148:151], v[202:205], v[36:39]
	v_mfma_f32_16x16x32_bf16 v[32:35], v[156:159], v[202:205], v[32:35]
	v_mfma_f32_16x16x32_bf16 v[20:23], v[148:151], v[210:213], v[20:23]
	v_mfma_f32_16x16x32_bf16 v[16:19], v[156:159], v[210:213], v[16:19]
	s_mov_b32 m0, s36
	v_lshl_add_u64 v[216:217], s[28:29], 0, v[132:133]
	s_setprio 0
	s_setprio 1
	v_mfma_f32_16x16x32_bf16 v[44:47], v[164:167], v[180:183], v[44:47]
	global_load_lds_dwordx4 v130, s[30:31]
	v_lshl_add_u64 v[218:219], s[30:31], 0, v[128:129]
	v_lshl_add_u64 v[220:221], s[30:31], 0, v[130:131]
	v_mfma_f32_16x16x32_bf16 v[40:43], v[172:175], v[180:183], v[40:43]
	v_mfma_f32_16x16x32_bf16 v[28:31], v[164:167], v[190:193], v[28:31]
	v_mfma_f32_16x16x32_bf16 v[24:27], v[172:175], v[190:193], v[24:27]
	v_mfma_f32_16x16x32_bf16 v[12:15], v[164:167], v[198:201], v[12:15]
	v_mfma_f32_16x16x32_bf16 v[8:11], v[172:175], v[198:201], v[8:11]
	v_mfma_f32_16x16x32_bf16 v[4:7], v[164:167], v[206:209], v[4:7]
	v_mfma_f32_16x16x32_bf16 v[0:3], v[172:175], v[206:209], v[0:3]
	v_mfma_f32_16x16x32_bf16 v[44:47], v[168:171], v[186:189], v[44:47]
	v_mfma_f32_16x16x32_bf16 v[40:43], v[176:179], v[186:189], v[40:43]
	v_mfma_f32_16x16x32_bf16 v[28:31], v[168:171], v[194:197], v[28:31]
	v_mfma_f32_16x16x32_bf16 v[24:27], v[176:179], v[194:197], v[24:27]
	v_mfma_f32_16x16x32_bf16 v[12:15], v[168:171], v[202:205], v[12:15]
	v_mfma_f32_16x16x32_bf16 v[8:11], v[176:179], v[202:205], v[8:11]
	v_mfma_f32_16x16x32_bf16 v[4:7], v[168:171], v[210:213], v[4:7]
	v_mfma_f32_16x16x32_bf16 v[0:3], v[176:179], v[210:213], v[0:3]
	s_setprio 0
	s_barrier
	ds_read_b128 v[144:147], v142 offset:32768
	ds_read_b128 v[148:151], v142 offset:33792
	ds_read_b128 v[152:155], v142 offset:34816
	ds_read_b128 v[156:159], v142 offset:35840
	ds_read_b128 v[164:167], v142 offset:49152
	ds_read_b128 v[168:171], v142 offset:50176
	ds_read_b128 v[172:175], v142 offset:51200
	ds_read_b128 v[176:179], v142 offset:52224
	s_add_u32 s30, s30, 0x40000
	s_addc_u32 s31, s31, 0
	s_mov_b32 m0, s37
	ds_read_b128 v[180:183], v143 offset:32768
	ds_read_b128 v[186:189], v143 offset:33792
	ds_read_b128 v[190:193], v143 offset:34816
	ds_read_b128 v[194:197], v143 offset:35840
	ds_read_b128 v[198:201], v143 offset:36864
	ds_read_b128 v[202:205], v143 offset:37888
	ds_read_b128 v[206:209], v143 offset:38912
	ds_read_b128 v[210:213], v143 offset:39936
	global_load_lds_dwordx4 v128, s[30:31]
	s_mov_b32 m0, s38
	s_nop 0
	global_load_lds_dwordx4 v130, s[30:31]
	s_waitcnt vmcnt(8)
	s_waitcnt lgkmcnt(0)
	s_barrier
	s_setprio 1
	s_waitcnt lgkmcnt(0)
	v_mfma_f32_16x16x32_bf16 v[124:127], v[144:147], v[180:183], v[124:127]
	v_mfma_f32_16x16x32_bf16 v[120:123], v[152:155], v[180:183], v[120:123]
	v_mfma_f32_16x16x32_bf16 v[116:119], v[144:147], v[190:193], v[116:119]
	v_mfma_f32_16x16x32_bf16 v[112:115], v[152:155], v[190:193], v[112:115]
	v_mfma_f32_16x16x32_bf16 v[100:103], v[144:147], v[198:201], v[100:103]
	v_mfma_f32_16x16x32_bf16 v[96:99], v[152:155], v[198:201], v[96:99]
	v_mfma_f32_16x16x32_bf16 v[84:87], v[144:147], v[206:209], v[84:87]
	v_mfma_f32_16x16x32_bf16 v[80:83], v[152:155], v[206:209], v[80:83]
	v_mfma_f32_16x16x32_bf16 v[124:127], v[148:151], v[186:189], v[124:127]
	v_mfma_f32_16x16x32_bf16 v[120:123], v[156:159], v[186:189], v[120:123]
	v_mfma_f32_16x16x32_bf16 v[116:119], v[148:151], v[194:197], v[116:119]
	v_mfma_f32_16x16x32_bf16 v[112:115], v[156:159], v[194:197], v[112:115]
	v_mfma_f32_16x16x32_bf16 v[100:103], v[148:151], v[202:205], v[100:103]
	v_mfma_f32_16x16x32_bf16 v[96:99], v[156:159], v[202:205], v[96:99]
	v_mfma_f32_16x16x32_bf16 v[84:87], v[148:151], v[210:213], v[84:87]
	v_mfma_f32_16x16x32_bf16 v[80:83], v[156:159], v[210:213], v[80:83]
	s_setprio 0
	s_setprio 1
	v_mfma_f32_16x16x32_bf16 v[108:111], v[164:167], v[180:183], v[108:111]
	v_mfma_f32_16x16x32_bf16 v[104:107], v[172:175], v[180:183], v[104:107]
	v_mfma_f32_16x16x32_bf16 v[92:95], v[164:167], v[190:193], v[92:95]
	v_mfma_f32_16x16x32_bf16 v[88:91], v[172:175], v[190:193], v[88:91]
	v_mfma_f32_16x16x32_bf16 v[76:79], v[164:167], v[198:201], v[76:79]
	v_mfma_f32_16x16x32_bf16 v[72:75], v[172:175], v[198:201], v[72:75]
	v_mfma_f32_16x16x32_bf16 v[68:71], v[164:167], v[206:209], v[68:71]
	v_mfma_f32_16x16x32_bf16 v[64:67], v[172:175], v[206:209], v[64:67]
	v_mfma_f32_16x16x32_bf16 v[108:111], v[168:171], v[186:189], v[108:111]
	v_mfma_f32_16x16x32_bf16 v[104:107], v[176:179], v[186:189], v[104:107]
	v_mfma_f32_16x16x32_bf16 v[92:95], v[168:171], v[194:197], v[92:95]
	v_mfma_f32_16x16x32_bf16 v[88:91], v[176:179], v[194:197], v[88:91]
	v_mfma_f32_16x16x32_bf16 v[76:79], v[168:171], v[202:205], v[76:79]
	v_mfma_f32_16x16x32_bf16 v[72:75], v[176:179], v[202:205], v[72:75]
	v_mfma_f32_16x16x32_bf16 v[68:71], v[168:171], v[210:213], v[68:71]
	v_mfma_f32_16x16x32_bf16 v[64:67], v[176:179], v[210:213], v[64:67]
	s_setprio 0
	s_barrier
	s_mov_b32 m0, s40
	v_lshl_add_u64 v[214:215], v[214:215], 0, s[6:7]
	ds_read_b128 v[180:183], v143 offset:49152
	ds_read_b128 v[186:189], v143 offset:50176
	ds_read_b128 v[190:193], v143 offset:51200
	ds_read_b128 v[194:197], v143 offset:52224
	ds_read_b128 v[198:201], v143 offset:53248
	ds_read_b128 v[202:205], v143 offset:54272
	ds_read_b128 v[206:209], v143 offset:55296
	ds_read_b128 v[210:213], v143 offset:56320
	global_load_lds_dwordx4 v[214:215], off
	v_lshl_add_u64 v[214:215], v[216:217], 0, s[6:7]
	s_mov_b32 m0, s41
	s_add_u32 s28, s28, 0x40080
	global_load_lds_dwordx4 v[214:215], off
	s_addc_u32 s29, s29, 0
	s_mov_b32 m0, s44
	v_lshl_add_u64 v[214:215], v[218:219], 0, s[6:7]
	global_load_lds_dwordx4 v138, s[28:29]
	s_mov_b32 m0, s45
	s_nop 0
	global_load_lds_dwordx4 v132, s[28:29]
	s_waitcnt vmcnt(6)
	s_waitcnt lgkmcnt(0)
	s_barrier
	s_setprio 1
	s_waitcnt lgkmcnt(0)
	v_mfma_f32_16x16x32_bf16 v[60:63], v[144:147], v[180:183], v[60:63]
	v_mfma_f32_16x16x32_bf16 v[56:59], v[152:155], v[180:183], v[56:59]
	s_mov_b32 m0, s42
	v_mfma_f32_16x16x32_bf16 v[52:55], v[144:147], v[190:193], v[52:55]
	global_load_lds_dwordx4 v[214:215], off
	v_mfma_f32_16x16x32_bf16 v[48:51], v[152:155], v[190:193], v[48:51]
	v_mfma_f32_16x16x32_bf16 v[36:39], v[144:147], v[198:201], v[36:39]
	v_mfma_f32_16x16x32_bf16 v[32:35], v[152:155], v[198:201], v[32:35]
	v_mfma_f32_16x16x32_bf16 v[20:23], v[144:147], v[206:209], v[20:23]
	v_mfma_f32_16x16x32_bf16 v[16:19], v[152:155], v[206:209], v[16:19]
	v_mfma_f32_16x16x32_bf16 v[60:63], v[148:151], v[186:189], v[60:63]
	v_mfma_f32_16x16x32_bf16 v[56:59], v[156:159], v[186:189], v[56:59]
	v_mfma_f32_16x16x32_bf16 v[52:55], v[148:151], v[194:197], v[52:55]
	v_mfma_f32_16x16x32_bf16 v[48:51], v[156:159], v[194:197], v[48:51]
	v_mfma_f32_16x16x32_bf16 v[36:39], v[148:151], v[202:205], v[36:39]
	v_mfma_f32_16x16x32_bf16 v[32:35], v[156:159], v[202:205], v[32:35]
	v_mfma_f32_16x16x32_bf16 v[20:23], v[148:151], v[210:213], v[20:23]
	v_mfma_f32_16x16x32_bf16 v[16:19], v[156:159], v[210:213], v[16:19]
	v_lshl_add_u64 v[214:215], v[220:221], 0, s[6:7]
	s_mov_b32 m0, s43
	s_setprio 0
	s_setprio 1
	v_mfma_f32_16x16x32_bf16 v[44:47], v[164:167], v[180:183], v[44:47]
	global_load_lds_dwordx4 v[214:215], off
	v_mfma_f32_16x16x32_bf16 v[40:43], v[172:175], v[180:183], v[40:43]
	v_mfma_f32_16x16x32_bf16 v[28:31], v[164:167], v[190:193], v[28:31]
	v_mfma_f32_16x16x32_bf16 v[24:27], v[172:175], v[190:193], v[24:27]
	v_mfma_f32_16x16x32_bf16 v[12:15], v[164:167], v[198:201], v[12:15]
	v_mfma_f32_16x16x32_bf16 v[8:11], v[172:175], v[198:201], v[8:11]
	v_mfma_f32_16x16x32_bf16 v[4:7], v[164:167], v[206:209], v[4:7]
	v_mfma_f32_16x16x32_bf16 v[0:3], v[172:175], v[206:209], v[0:3]
	v_mfma_f32_16x16x32_bf16 v[44:47], v[168:171], v[186:189], v[44:47]
	s_add_i32 s53, s53, 2
	v_mfma_f32_16x16x32_bf16 v[40:43], v[176:179], v[186:189], v[40:43]
	s_add_u32 s26, s26, 0x100
	v_mfma_f32_16x16x32_bf16 v[28:31], v[168:171], v[194:197], v[28:31]
	s_addc_u32 s27, s27, 0
	v_mfma_f32_16x16x32_bf16 v[24:27], v[176:179], v[194:197], v[24:27]
	s_add_u32 s51, s51, 0x100
	v_mfma_f32_16x16x32_bf16 v[12:15], v[168:171], v[202:205], v[12:15]
	s_addc_u32 s52, s52, 0
	v_mfma_f32_16x16x32_bf16 v[8:11], v[176:179], v[202:205], v[8:11]
	s_cmp_gt_u32 s53, 13
	v_mfma_f32_16x16x32_bf16 v[4:7], v[168:171], v[210:213], v[4:7]
	v_mfma_f32_16x16x32_bf16 v[0:3], v[176:179], v[210:213], v[0:3]
	s_setprio 0
	s_barrier
	s_cbranch_scc0 .LBB0_206
	s_and_b64 vcc, exec, s[8:9]
	s_cbranch_vccz .LBB0_209
	s_barrier

.LBB0_459:
	ds_read_b128 v[144:147], v142
	ds_read_b128 v[148:151], v142 offset:1024
	ds_read_b128 v[152:155], v142 offset:2048
	ds_read_b128 v[156:159], v142 offset:3072
	ds_read_b128 v[164:167], v142 offset:16384
	ds_read_b128 v[168:171], v142 offset:17408
	ds_read_b128 v[172:175], v142 offset:18432
	ds_read_b128 v[176:179], v142 offset:19456
	s_add_u32 s23, s26, 0xfff80080
	s_addc_u32 s28, s27, -1
	s_cmp_eq_u32 s54, 28
	s_cselect_b32 s31, s13, s28
	s_cselect_b32 s30, s50, s23
	s_cselect_b32 s29, s11, s53
	s_cselect_b32 s28, s51, s52
	s_add_i32 m0, s15, 0xc000
	ds_read_b128 v[180:183], v143
	ds_read_b128 v[188:191], v143 offset:1024
	ds_read_b128 v[192:195], v143 offset:2048
	ds_read_b128 v[196:199], v143 offset:3072
	ds_read_b128 v[200:203], v143 offset:4096
	ds_read_b128 v[204:207], v143 offset:5120
	ds_read_b128 v[208:211], v143 offset:6144
	ds_read_b128 v[212:215], v143 offset:7168
	global_load_lds_dwordx4 v128, s[26:27]
	s_add_i32 m0, s15, 0xe000
	v_mov_b32_e32 v131, v129
	global_load_lds_dwordx4 v130, s[26:27]
	s_waitcnt vmcnt(8)
	s_waitcnt lgkmcnt(0)
	s_barrier
	s_setprio 1
	s_waitcnt lgkmcnt(0)
	v_mfma_f32_16x16x32_bf16 v[124:127], v[144:147], v[180:183], v[124:127]
	v_mfma_f32_16x16x32_bf16 v[120:123], v[152:155], v[180:183], v[120:123]
	v_mfma_f32_16x16x32_bf16 v[116:119], v[144:147], v[192:195], v[116:119]
	v_mfma_f32_16x16x32_bf16 v[112:115], v[152:155], v[192:195], v[112:115]
	v_mfma_f32_16x16x32_bf16 v[100:103], v[144:147], v[200:203], v[100:103]
	v_mfma_f32_16x16x32_bf16 v[96:99], v[152:155], v[200:203], v[96:99]
	v_mfma_f32_16x16x32_bf16 v[84:87], v[144:147], v[208:211], v[84:87]
	v_mfma_f32_16x16x32_bf16 v[80:83], v[152:155], v[208:211], v[80:83]
	v_mfma_f32_16x16x32_bf16 v[124:127], v[148:151], v[188:191], v[124:127]
	v_mfma_f32_16x16x32_bf16 v[120:123], v[156:159], v[188:191], v[120:123]
	v_mfma_f32_16x16x32_bf16 v[116:119], v[148:151], v[196:199], v[116:119]
	v_mfma_f32_16x16x32_bf16 v[112:115], v[156:159], v[196:199], v[112:115]
	v_mfma_f32_16x16x32_bf16 v[100:103], v[148:151], v[204:207], v[100:103]
	v_mfma_f32_16x16x32_bf16 v[96:99], v[156:159], v[204:207], v[96:99]
	v_mfma_f32_16x16x32_bf16 v[84:87], v[148:151], v[212:215], v[84:87]
	v_mfma_f32_16x16x32_bf16 v[80:83], v[156:159], v[212:215], v[80:83]
	s_setprio 0
	s_setprio 1
	v_mfma_f32_16x16x32_bf16 v[108:111], v[164:167], v[180:183], v[108:111]
	v_mfma_f32_16x16x32_bf16 v[104:107], v[172:175], v[180:183], v[104:107]
	v_mfma_f32_16x16x32_bf16 v[92:95], v[164:167], v[192:195], v[92:95]
	v_mfma_f32_16x16x32_bf16 v[88:91], v[172:175], v[192:195], v[88:91]
	v_mfma_f32_16x16x32_bf16 v[76:79], v[164:167], v[200:203], v[76:79]
	v_mfma_f32_16x16x32_bf16 v[72:75], v[172:175], v[200:203], v[72:75]
	v_mfma_f32_16x16x32_bf16 v[68:71], v[164:167], v[208:211], v[68:71]
	v_mfma_f32_16x16x32_bf16 v[64:67], v[172:175], v[208:211], v[64:67]
	v_mfma_f32_16x16x32_bf16 v[108:111], v[168:171], v[188:191], v[108:111]
	v_mfma_f32_16x16x32_bf16 v[104:107], v[176:179], v[188:191], v[104:107]
	v_mfma_f32_16x16x32_bf16 v[92:95], v[168:171], v[196:199], v[92:95]
	v_mfma_f32_16x16x32_bf16 v[88:91], v[176:179], v[196:199], v[88:91]
	v_mfma_f32_16x16x32_bf16 v[76:79], v[168:171], v[204:207], v[76:79]
	v_mfma_f32_16x16x32_bf16 v[72:75], v[176:179], v[204:207], v[72:75]
	v_mfma_f32_16x16x32_bf16 v[68:71], v[168:171], v[212:215], v[68:71]
	v_mfma_f32_16x16x32_bf16 v[64:67], v[176:179], v[212:215], v[64:67]
	s_setprio 0
	s_barrier
	s_mov_b32 m0, s34
	ds_read_b128 v[180:183], v143 offset:16384
	ds_read_b128 v[188:191], v143 offset:17408
	ds_read_b128 v[192:195], v143 offset:18432
	ds_read_b128 v[196:199], v143 offset:19456
	ds_read_b128 v[200:203], v143 offset:20480
	ds_read_b128 v[204:207], v143 offset:21504
	ds_read_b128 v[208:211], v143 offset:22528
	ds_read_b128 v[212:215], v143 offset:23552
	global_load_lds_dwordx4 v138, s[28:29]
	s_mov_b32 m0, s35
	s_add_u32 s86, s28, 0x80000
	global_load_lds_dwordx4 v132, s[28:29]
	s_addc_u32 s87, s29, 0
	s_mov_b32 m0, s36
	v_mov_b32_e32 v139, v129
	global_load_lds_dwordx4 v138, s[86:87]
	s_mov_b32 m0, s37
	v_mov_b32_e32 v133, v129
	global_load_lds_dwordx4 v132, s[86:87]
	s_waitcnt vmcnt(6)
	s_waitcnt lgkmcnt(0)
	s_barrier
	s_setprio 1
	s_waitcnt lgkmcnt(0)
	v_mfma_f32_16x16x32_bf16 v[60:63], v[144:147], v[180:183], v[60:63]
	v_mfma_f32_16x16x32_bf16 v[56:59], v[152:155], v[180:183], v[56:59]
	s_mov_b32 m0, s15
	v_lshl_add_u64 v[216:217], s[28:29], 0, v[138:139]
	v_mfma_f32_16x16x32_bf16 v[52:55], v[144:147], v[192:195], v[52:55]
	global_load_lds_dwordx4 v128, s[30:31]
	v_mfma_f32_16x16x32_bf16 v[48:51], v[152:155], v[192:195], v[48:51]
	v_mfma_f32_16x16x32_bf16 v[36:39], v[144:147], v[200:203], v[36:39]
	v_mfma_f32_16x16x32_bf16 v[32:35], v[152:155], v[200:203], v[32:35]
	v_mfma_f32_16x16x32_bf16 v[20:23], v[144:147], v[208:211], v[20:23]
	v_mfma_f32_16x16x32_bf16 v[16:19], v[152:155], v[208:211], v[16:19]
	v_mfma_f32_16x16x32_bf16 v[60:63], v[148:151], v[188:191], v[60:63]
	v_mfma_f32_16x16x32_bf16 v[56:59], v[156:159], v[188:191], v[56:59]
	v_mfma_f32_16x16x32_bf16 v[52:55], v[148:151], v[196:199], v[52:55]
	v_mfma_f32_16x16x32_bf16 v[48:51], v[156:159], v[196:199], v[48:51]
	v_mfma_f32_16x16x32_bf16 v[36:39], v[148:151], v[204:207], v[36:39]
	v_mfma_f32_16x16x32_bf16 v[32:35], v[156:159], v[204:207], v[32:35]
	v_mfma_f32_16x16x32_bf16 v[20:23], v[148:151], v[212:215], v[20:23]
	v_mfma_f32_16x16x32_bf16 v[16:19], v[156:159], v[212:215], v[16:19]
	s_mov_b32 m0, s38
	v_lshl_add_u64 v[218:219], s[28:29], 0, v[132:133]
	s_setprio 0
	s_setprio 1
	v_mfma_f32_16x16x32_bf16 v[44:47], v[164:167], v[180:183], v[44:47]
	global_load_lds_dwordx4 v130, s[30:31]
	v_lshl_add_u64 v[220:221], s[30:31], 0, v[128:129]
	v_lshl_add_u64 v[222:223], s[30:31], 0, v[130:131]
	v_mfma_f32_16x16x32_bf16 v[40:43], v[172:175], v[180:183], v[40:43]
	v_mfma_f32_16x16x32_bf16 v[28:31], v[164:167], v[192:195], v[28:31]
	v_mfma_f32_16x16x32_bf16 v[24:27], v[172:175], v[192:195], v[24:27]
	v_mfma_f32_16x16x32_bf16 v[12:15], v[164:167], v[200:203], v[12:15]
	v_mfma_f32_16x16x32_bf16 v[8:11], v[172:175], v[200:203], v[8:11]
	v_mfma_f32_16x16x32_bf16 v[4:7], v[164:167], v[208:211], v[4:7]
	v_mfma_f32_16x16x32_bf16 v[0:3], v[172:175], v[208:211], v[0:3]
	v_mfma_f32_16x16x32_bf16 v[44:47], v[168:171], v[188:191], v[44:47]
	v_mfma_f32_16x16x32_bf16 v[40:43], v[176:179], v[188:191], v[40:43]
	v_mfma_f32_16x16x32_bf16 v[28:31], v[168:171], v[196:199], v[28:31]
	v_mfma_f32_16x16x32_bf16 v[24:27], v[176:179], v[196:199], v[24:27]
	v_mfma_f32_16x16x32_bf16 v[12:15], v[168:171], v[204:207], v[12:15]
	v_mfma_f32_16x16x32_bf16 v[8:11], v[176:179], v[204:207], v[8:11]
	v_mfma_f32_16x16x32_bf16 v[4:7], v[168:171], v[212:215], v[4:7]
	v_mfma_f32_16x16x32_bf16 v[0:3], v[176:179], v[212:215], v[0:3]
	s_setprio 0
	s_barrier
	ds_read_b128 v[144:147], v142 offset:32768
	ds_read_b128 v[148:151], v142 offset:33792
	ds_read_b128 v[152:155], v142 offset:34816
	ds_read_b128 v[156:159], v142 offset:35840
	ds_read_b128 v[164:167], v142 offset:49152
	ds_read_b128 v[168:171], v142 offset:50176
	ds_read_b128 v[172:175], v142 offset:51200
	ds_read_b128 v[176:179], v142 offset:52224
	s_add_u32 s30, s30, 0x80000
	s_addc_u32 s31, s31, 0
	s_mov_b32 m0, s39
	ds_read_b128 v[180:183], v143 offset:32768
	ds_read_b128 v[188:191], v143 offset:33792
	ds_read_b128 v[192:195], v143 offset:34816
	ds_read_b128 v[196:199], v143 offset:35840
	ds_read_b128 v[200:203], v143 offset:36864
	ds_read_b128 v[204:207], v143 offset:37888
	ds_read_b128 v[208:211], v143 offset:38912
	ds_read_b128 v[212:215], v143 offset:39936
	global_load_lds_dwordx4 v128, s[30:31]
	s_mov_b32 m0, s40
	s_nop 0
	global_load_lds_dwordx4 v130, s[30:31]
	s_waitcnt vmcnt(8)
	s_waitcnt lgkmcnt(0)
	s_barrier
	s_setprio 1
	s_waitcnt lgkmcnt(0)
	v_mfma_f32_16x16x32_bf16 v[124:127], v[144:147], v[180:183], v[124:127]
	v_mfma_f32_16x16x32_bf16 v[120:123], v[152:155], v[180:183], v[120:123]
	v_mfma_f32_16x16x32_bf16 v[116:119], v[144:147], v[192:195], v[116:119]
	v_mfma_f32_16x16x32_bf16 v[112:115], v[152:155], v[192:195], v[112:115]
	v_mfma_f32_16x16x32_bf16 v[100:103], v[144:147], v[200:203], v[100:103]
	v_mfma_f32_16x16x32_bf16 v[96:99], v[152:155], v[200:203], v[96:99]
	v_mfma_f32_16x16x32_bf16 v[84:87], v[144:147], v[208:211], v[84:87]
	v_mfma_f32_16x16x32_bf16 v[80:83], v[152:155], v[208:211], v[80:83]
	v_mfma_f32_16x16x32_bf16 v[124:127], v[148:151], v[188:191], v[124:127]
	v_mfma_f32_16x16x32_bf16 v[120:123], v[156:159], v[188:191], v[120:123]
	v_mfma_f32_16x16x32_bf16 v[116:119], v[148:151], v[196:199], v[116:119]
	v_mfma_f32_16x16x32_bf16 v[112:115], v[156:159], v[196:199], v[112:115]
	v_mfma_f32_16x16x32_bf16 v[100:103], v[148:151], v[204:207], v[100:103]
	v_mfma_f32_16x16x32_bf16 v[96:99], v[156:159], v[204:207], v[96:99]
	v_mfma_f32_16x16x32_bf16 v[84:87], v[148:151], v[212:215], v[84:87]
	v_mfma_f32_16x16x32_bf16 v[80:83], v[156:159], v[212:215], v[80:83]
	s_setprio 0
	s_setprio 1
	v_mfma_f32_16x16x32_bf16 v[108:111], v[164:167], v[180:183], v[108:111]
	v_mfma_f32_16x16x32_bf16 v[104:107], v[172:175], v[180:183], v[104:107]
	v_mfma_f32_16x16x32_bf16 v[92:95], v[164:167], v[192:195], v[92:95]
	v_mfma_f32_16x16x32_bf16 v[88:91], v[172:175], v[192:195], v[88:91]
	v_mfma_f32_16x16x32_bf16 v[76:79], v[164:167], v[200:203], v[76:79]
	v_mfma_f32_16x16x32_bf16 v[72:75], v[172:175], v[200:203], v[72:75]
	v_mfma_f32_16x16x32_bf16 v[68:71], v[164:167], v[208:211], v[68:71]
	v_mfma_f32_16x16x32_bf16 v[64:67], v[172:175], v[208:211], v[64:67]
	v_mfma_f32_16x16x32_bf16 v[108:111], v[168:171], v[188:191], v[108:111]
	v_mfma_f32_16x16x32_bf16 v[104:107], v[176:179], v[188:191], v[104:107]
	v_mfma_f32_16x16x32_bf16 v[92:95], v[168:171], v[196:199], v[92:95]
	v_mfma_f32_16x16x32_bf16 v[88:91], v[176:179], v[196:199], v[88:91]
	v_mfma_f32_16x16x32_bf16 v[76:79], v[168:171], v[204:207], v[76:79]
	v_mfma_f32_16x16x32_bf16 v[72:75], v[176:179], v[204:207], v[72:75]
	v_mfma_f32_16x16x32_bf16 v[68:71], v[168:171], v[212:215], v[68:71]
	v_mfma_f32_16x16x32_bf16 v[64:67], v[176:179], v[212:215], v[64:67]
	s_setprio 0
	s_barrier
	s_mov_b32 m0, s42
	v_lshl_add_u64 v[216:217], v[216:217], 0, s[6:7]
	ds_read_b128 v[180:183], v143 offset:49152
	ds_read_b128 v[188:191], v143 offset:50176
	ds_read_b128 v[192:195], v143 offset:51200
	ds_read_b128 v[196:199], v143 offset:52224
	ds_read_b128 v[200:203], v143 offset:53248
	ds_read_b128 v[204:207], v143 offset:54272
	ds_read_b128 v[208:211], v143 offset:55296
	ds_read_b128 v[212:215], v143 offset:56320
	global_load_lds_dwordx4 v[216:217], off
	v_lshl_add_u64 v[216:217], v[218:219], 0, s[6:7]
	s_mov_b32 m0, s43
	s_add_u32 s28, s28, 0x80080
	global_load_lds_dwordx4 v[216:217], off
	s_addc_u32 s29, s29, 0
	s_mov_b32 m0, s47
	v_lshl_add_u64 v[216:217], v[220:221], 0, s[6:7]
	global_load_lds_dwordx4 v138, s[28:29]
	s_mov_b32 m0, s48
	s_nop 0
	global_load_lds_dwordx4 v132, s[28:29]
	s_waitcnt vmcnt(6)
	s_waitcnt lgkmcnt(0)
	s_barrier
	s_setprio 1
	s_waitcnt lgkmcnt(0)
	v_mfma_f32_16x16x32_bf16 v[60:63], v[144:147], v[180:183], v[60:63]
	v_mfma_f32_16x16x32_bf16 v[56:59], v[152:155], v[180:183], v[56:59]
	s_mov_b32 m0, s44
	v_mfma_f32_16x16x32_bf16 v[52:55], v[144:147], v[192:195], v[52:55]
	global_load_lds_dwordx4 v[216:217], off
	v_mfma_f32_16x16x32_bf16 v[48:51], v[152:155], v[192:195], v[48:51]
	v_mfma_f32_16x16x32_bf16 v[36:39], v[144:147], v[200:203], v[36:39]
	v_mfma_f32_16x16x32_bf16 v[32:35], v[152:155], v[200:203], v[32:35]
	v_mfma_f32_16x16x32_bf16 v[20:23], v[144:147], v[208:211], v[20:23]
	v_mfma_f32_16x16x32_bf16 v[16:19], v[152:155], v[208:211], v[16:19]
	v_mfma_f32_16x16x32_bf16 v[60:63], v[148:151], v[188:191], v[60:63]
	v_mfma_f32_16x16x32_bf16 v[56:59], v[156:159], v[188:191], v[56:59]
	v_mfma_f32_16x16x32_bf16 v[52:55], v[148:151], v[196:199], v[52:55]
	v_mfma_f32_16x16x32_bf16 v[48:51], v[156:159], v[196:199], v[48:51]
	v_mfma_f32_16x16x32_bf16 v[36:39], v[148:151], v[204:207], v[36:39]
	v_mfma_f32_16x16x32_bf16 v[32:35], v[156:159], v[204:207], v[32:35]
	v_mfma_f32_16x16x32_bf16 v[20:23], v[148:151], v[212:215], v[20:23]
	v_mfma_f32_16x16x32_bf16 v[16:19], v[156:159], v[212:215], v[16:19]
	v_lshl_add_u64 v[216:217], v[222:223], 0, s[6:7]
	s_mov_b32 m0, s45
	s_setprio 0
	s_setprio 1
	v_mfma_f32_16x16x32_bf16 v[44:47], v[164:167], v[180:183], v[44:47]
	global_load_lds_dwordx4 v[216:217], off
	v_mfma_f32_16x16x32_bf16 v[40:43], v[172:175], v[180:183], v[40:43]
	v_mfma_f32_16x16x32_bf16 v[28:31], v[164:167], v[192:195], v[28:31]
	v_mfma_f32_16x16x32_bf16 v[24:27], v[172:175], v[192:195], v[24:27]
	v_mfma_f32_16x16x32_bf16 v[12:15], v[164:167], v[200:203], v[12:15]
	v_mfma_f32_16x16x32_bf16 v[8:11], v[172:175], v[200:203], v[8:11]
	v_mfma_f32_16x16x32_bf16 v[4:7], v[164:167], v[208:211], v[4:7]
	v_mfma_f32_16x16x32_bf16 v[0:3], v[172:175], v[208:211], v[0:3]
	v_mfma_f32_16x16x32_bf16 v[44:47], v[168:171], v[188:191], v[44:47]
	s_add_i32 s54, s54, 2
	v_mfma_f32_16x16x32_bf16 v[40:43], v[176:179], v[188:191], v[40:43]
	s_add_u32 s26, s26, 0x100
	v_mfma_f32_16x16x32_bf16 v[28:31], v[168:171], v[196:199], v[28:31]
	s_addc_u32 s27, s27, 0
	v_mfma_f32_16x16x32_bf16 v[24:27], v[176:179], v[196:199], v[24:27]
	s_add_u32 s52, s52, 0x100
	v_mfma_f32_16x16x32_bf16 v[12:15], v[168:171], v[204:207], v[12:15]
	s_addc_u32 s53, s53, 0
	v_mfma_f32_16x16x32_bf16 v[8:11], v[176:179], v[204:207], v[8:11]
	s_cmp_gt_u32 s54, 29
	v_mfma_f32_16x16x32_bf16 v[4:7], v[168:171], v[212:215], v[4:7]
	v_mfma_f32_16x16x32_bf16 v[0:3], v[176:179], v[212:215], v[0:3]
	s_setprio 0
	s_barrier
	s_cbranch_scc0 .LBB0_459
	s_and_b64 vcc, exec, s[8:9]
	s_cbranch_vccz .LBB0_462
	s_barrier

.LBB0_585:
	ds_read_b128 v[24:27], v189
	ds_read_b128 v[28:31], v189 offset:16
	ds_read_b128 v[16:19], v189 offset:2048
	ds_read_b128 v[20:23], v189 offset:2064
	ds_read_b128 v[8:11], v189 offset:16384
	ds_read_b128 v[12:15], v189 offset:16400
	ds_read_b128 v[0:3], v189 offset:18432
	ds_read_b128 v[4:7], v189 offset:18448
	s_add_u32 s23, s30, 0xfffe0080
	s_addc_u32 s34, s31, -1
	s_cmp_eq_u32 s64, 4
	s_cselect_b32 s37, s21, s34
	s_cselect_b32 s36, s53, s23
	s_cselect_b32 s35, s15, s63
	s_cselect_b32 s34, s54, s55
	s_add_i32 m0, s11, 0xc000
	ds_read_b128 v[176:179], v190
	ds_read_b128 v[180:183], v190 offset:16
	ds_read_b128 v[192:195], v190 offset:2048
	ds_read_b128 v[196:199], v190 offset:2064
	ds_read_b128 v[200:203], v190 offset:4096
	ds_read_b128 v[204:207], v190 offset:4112
	ds_read_b128 v[208:211], v190 offset:6144
	ds_read_b128 v[212:215], v190 offset:6160
	global_load_lds_dwordx4 v164, s[30:31]
	s_add_i32 m0, s11, 0xe000
	v_mov_b32_e32 v169, v165
	global_load_lds_dwordx4 v168, s[30:31]
	s_waitcnt vmcnt(8)
	s_waitcnt lgkmcnt(0)
	s_barrier
	s_setprio 1
	s_waitcnt lgkmcnt(0)
	v_mfma_f32_16x16x128_f8f6f4 v[156:159], v[24:31], v[176:183], v[156:159]
	v_mfma_f32_16x16x128_f8f6f4 v[148:151], v[16:23], v[176:183], v[148:151]
	v_mfma_f32_16x16x128_f8f6f4 v[140:143], v[24:31], v[192:199], v[140:143]
	v_mfma_f32_16x16x128_f8f6f4 v[132:135], v[16:23], v[192:199], v[132:135]
	v_mfma_f32_16x16x128_f8f6f4 v[124:127], v[24:31], v[200:207], v[124:127]
	v_mfma_f32_16x16x128_f8f6f4 v[116:119], v[16:23], v[200:207], v[116:119]
	v_mfma_f32_16x16x128_f8f6f4 v[108:111], v[24:31], v[208:215], v[108:111]
	v_mfma_f32_16x16x128_f8f6f4 v[100:103], v[16:23], v[208:215], v[100:103]
	s_setprio 0
	s_setprio 1
	v_mfma_f32_16x16x128_f8f6f4 v[152:155], v[8:15], v[176:183], v[152:155]
	v_mfma_f32_16x16x128_f8f6f4 v[144:147], v[0:7], v[176:183], v[144:147]
	v_mfma_f32_16x16x128_f8f6f4 v[136:139], v[8:15], v[192:199], v[136:139]
	v_mfma_f32_16x16x128_f8f6f4 v[128:131], v[0:7], v[192:199], v[128:131]
	v_mfma_f32_16x16x128_f8f6f4 v[120:123], v[8:15], v[200:207], v[120:123]
	v_mfma_f32_16x16x128_f8f6f4 v[112:115], v[0:7], v[200:207], v[112:115]
	v_mfma_f32_16x16x128_f8f6f4 v[104:107], v[8:15], v[208:215], v[104:107]
	v_mfma_f32_16x16x128_f8f6f4 v[96:99], v[0:7], v[208:215], v[96:99]
	s_setprio 0
	s_barrier
	s_mov_b32 m0, s13
	ds_read_b128 v[192:195], v190 offset:16384
	ds_read_b128 v[196:199], v190 offset:16400
	ds_read_b128 v[200:203], v190 offset:18432
	ds_read_b128 v[204:207], v190 offset:18448
	ds_read_b128 v[208:211], v190 offset:20480
	ds_read_b128 v[212:215], v190 offset:20496
	ds_read_b128 v[216:219], v190 offset:22528
	ds_read_b128 v[220:223], v190 offset:22544
	global_load_lds_dwordx4 v166, s[34:35]
	s_mov_b32 m0, s22
	s_add_u32 s86, s34, 0x20000
	global_load_lds_dwordx4 v170, s[34:35]
	s_addc_u32 s87, s35, 0
	s_mov_b32 m0, s29
	v_mov_b32_e32 v167, v165
	global_load_lds_dwordx4 v166, s[86:87]
	s_mov_b32 m0, s38
	v_mov_b32_e32 v171, v165
	global_load_lds_dwordx4 v170, s[86:87]
	s_waitcnt vmcnt(6)
	s_waitcnt lgkmcnt(0)
	s_barrier
	s_setprio 1
	s_waitcnt lgkmcnt(0)
	v_mfma_f32_16x16x128_f8f6f4 v[92:95], v[24:31], v[192:199], v[92:95]
	v_mfma_f32_16x16x128_f8f6f4 v[84:87], v[16:23], v[192:199], v[84:87]
	s_mov_b32 m0, s11
	v_lshl_add_u64 v[182:183], s[34:35], 0, v[166:167]
	v_mfma_f32_16x16x128_f8f6f4 v[76:79], v[24:31], v[200:207], v[76:79]
	global_load_lds_dwordx4 v164, s[36:37]
	v_mfma_f32_16x16x128_f8f6f4 v[68:71], v[16:23], v[200:207], v[68:71]
	v_mfma_f32_16x16x128_f8f6f4 v[60:63], v[24:31], v[208:215], v[60:63]
	v_mfma_f32_16x16x128_f8f6f4 v[52:55], v[16:23], v[208:215], v[52:55]
	v_mfma_f32_16x16x128_f8f6f4 v[44:47], v[24:31], v[216:223], v[44:47]
	v_mfma_f32_16x16x128_f8f6f4 v[36:39], v[16:23], v[216:223], v[36:39]
	s_mov_b32 m0, s39
	v_lshl_add_u64 v[180:181], s[34:35], 0, v[170:171]
	s_setprio 0
	s_setprio 1
	v_mfma_f32_16x16x128_f8f6f4 v[88:91], v[8:15], v[192:199], v[88:91]
	global_load_lds_dwordx4 v168, s[36:37]
	v_lshl_add_u64 v[178:179], s[36:37], 0, v[164:165]
	v_lshl_add_u64 v[176:177], s[36:37], 0, v[168:169]
	v_mfma_f32_16x16x128_f8f6f4 v[80:83], v[0:7], v[192:199], v[80:83]
	v_mfma_f32_16x16x128_f8f6f4 v[72:75], v[8:15], v[200:207], v[72:75]
	v_mfma_f32_16x16x128_f8f6f4 v[64:67], v[0:7], v[200:207], v[64:67]
	v_mfma_f32_16x16x128_f8f6f4 v[56:59], v[8:15], v[208:215], v[56:59]
	v_mfma_f32_16x16x128_f8f6f4 v[48:51], v[0:7], v[208:215], v[48:51]
	v_mfma_f32_16x16x128_f8f6f4 v[40:43], v[8:15], v[216:223], v[40:43]
	v_mfma_f32_16x16x128_f8f6f4 v[32:35], v[0:7], v[216:223], v[32:35]
	s_setprio 0
	s_barrier
	ds_read_b128 v[0:3], v189 offset:32768
	ds_read_b128 v[4:7], v189 offset:32784
	ds_read_b128 v[8:11], v189 offset:34816
	ds_read_b128 v[12:15], v189 offset:34832
	ds_read_b128 v[16:19], v189 offset:49152
	ds_read_b128 v[20:23], v189 offset:49168
	ds_read_b128 v[24:27], v189 offset:51200
	ds_read_b128 v[28:31], v189 offset:51216
	s_add_u32 s36, s36, 0x20000
	s_addc_u32 s37, s37, 0
	s_mov_b32 m0, s40
	ds_read_b128 v[192:195], v190 offset:32768
	ds_read_b128 v[196:199], v190 offset:32784
	ds_read_b128 v[200:203], v190 offset:34816
	ds_read_b128 v[204:207], v190 offset:34832
	ds_read_b128 v[208:211], v190 offset:36864
	ds_read_b128 v[212:215], v190 offset:36880
	ds_read_b128 v[216:219], v190 offset:38912
	ds_read_b128 v[220:223], v190 offset:38928
	global_load_lds_dwordx4 v164, s[36:37]
	s_mov_b32 m0, s41
	s_nop 0
	global_load_lds_dwordx4 v168, s[36:37]
	s_waitcnt vmcnt(8)
	s_waitcnt lgkmcnt(0)
	s_barrier
	s_setprio 1
	s_waitcnt lgkmcnt(0)
	v_mfma_f32_16x16x128_f8f6f4 v[156:159], v[0:7], v[192:199], v[156:159]
	v_mfma_f32_16x16x128_f8f6f4 v[148:151], v[8:15], v[192:199], v[148:151]
	v_mfma_f32_16x16x128_f8f6f4 v[140:143], v[0:7], v[200:207], v[140:143]
	v_mfma_f32_16x16x128_f8f6f4 v[132:135], v[8:15], v[200:207], v[132:135]
	v_mfma_f32_16x16x128_f8f6f4 v[124:127], v[0:7], v[208:215], v[124:127]
	v_mfma_f32_16x16x128_f8f6f4 v[116:119], v[8:15], v[208:215], v[116:119]
	v_mfma_f32_16x16x128_f8f6f4 v[108:111], v[0:7], v[216:223], v[108:111]
	v_mfma_f32_16x16x128_f8f6f4 v[100:103], v[8:15], v[216:223], v[100:103]
	s_setprio 0
	s_setprio 1
	v_mfma_f32_16x16x128_f8f6f4 v[152:155], v[16:23], v[192:199], v[152:155]
	v_mfma_f32_16x16x128_f8f6f4 v[144:147], v[24:31], v[192:199], v[144:147]
	v_mfma_f32_16x16x128_f8f6f4 v[136:139], v[16:23], v[200:207], v[136:139]
	v_mfma_f32_16x16x128_f8f6f4 v[128:131], v[24:31], v[200:207], v[128:131]
	v_mfma_f32_16x16x128_f8f6f4 v[120:123], v[16:23], v[208:215], v[120:123]
	v_mfma_f32_16x16x128_f8f6f4 v[112:115], v[24:31], v[208:215], v[112:115]
	v_mfma_f32_16x16x128_f8f6f4 v[104:107], v[16:23], v[216:223], v[104:107]
	v_mfma_f32_16x16x128_f8f6f4 v[96:99], v[24:31], v[216:223], v[96:99]
	s_setprio 0
	s_barrier
	s_mov_b32 m0, s43
	v_lshl_add_u64 v[182:183], v[182:183], 0, s[6:7]
	ds_read_b128 v[192:195], v190 offset:49152
	ds_read_b128 v[196:199], v190 offset:49168
	ds_read_b128 v[200:203], v190 offset:51200
	ds_read_b128 v[204:207], v190 offset:51216
	ds_read_b128 v[208:211], v190 offset:53248
	ds_read_b128 v[212:215], v190 offset:53264
	ds_read_b128 v[216:219], v190 offset:55296
	ds_read_b128 v[220:223], v190 offset:55312
	global_load_lds_dwordx4 v[182:183], off
	v_lshl_add_u64 v[180:181], v[180:181], 0, s[6:7]
	s_mov_b32 m0, s44
	s_add_u32 s34, s34, 0x20080
	global_load_lds_dwordx4 v[180:181], off
	s_addc_u32 s35, s35, 0
	s_mov_b32 m0, s48
	v_lshl_add_u64 v[178:179], v[178:179], 0, s[6:7]
	global_load_lds_dwordx4 v166, s[34:35]
	s_mov_b32 m0, s49
	v_lshl_add_u64 v[176:177], v[176:177], 0, s[6:7]
	global_load_lds_dwordx4 v170, s[34:35]
	s_waitcnt vmcnt(6)
	s_waitcnt lgkmcnt(0)
	s_barrier
	s_setprio 1
	s_waitcnt lgkmcnt(0)
	v_mfma_f32_16x16x128_f8f6f4 v[92:95], v[0:7], v[192:199], v[92:95]
	v_mfma_f32_16x16x128_f8f6f4 v[84:87], v[8:15], v[192:199], v[84:87]
	s_mov_b32 m0, s45
	v_mfma_f32_16x16x128_f8f6f4 v[76:79], v[0:7], v[200:207], v[76:79]
	global_load_lds_dwordx4 v[178:179], off
	v_mfma_f32_16x16x128_f8f6f4 v[68:71], v[8:15], v[200:207], v[68:71]
	v_mfma_f32_16x16x128_f8f6f4 v[60:63], v[0:7], v[208:215], v[60:63]
	v_mfma_f32_16x16x128_f8f6f4 v[52:55], v[8:15], v[208:215], v[52:55]
	v_mfma_f32_16x16x128_f8f6f4 v[44:47], v[0:7], v[216:223], v[44:47]
	v_mfma_f32_16x16x128_f8f6f4 v[36:39], v[8:15], v[216:223], v[36:39]
	s_mov_b32 m0, s47
	s_setprio 0
	s_setprio 1
	v_mfma_f32_16x16x128_f8f6f4 v[88:91], v[16:23], v[192:199], v[88:91]
	s_add_i32 s64, s64, 2
	global_load_lds_dwordx4 v[176:177], off
	v_mfma_f32_16x16x128_f8f6f4 v[80:83], v[24:31], v[192:199], v[80:83]
	s_add_u32 s30, s30, 0x100
	v_mfma_f32_16x16x128_f8f6f4 v[72:75], v[16:23], v[200:207], v[72:75]
	s_addc_u32 s31, s31, 0
	v_mfma_f32_16x16x128_f8f6f4 v[64:67], v[24:31], v[200:207], v[64:67]
	s_add_u32 s55, s55, 0x100
	v_mfma_f32_16x16x128_f8f6f4 v[56:59], v[16:23], v[208:215], v[56:59]
	s_addc_u32 s63, s63, 0
	v_mfma_f32_16x16x128_f8f6f4 v[48:51], v[24:31], v[208:215], v[48:51]
	s_cmp_gt_u32 s64, 5
	v_mfma_f32_16x16x128_f8f6f4 v[40:43], v[16:23], v[216:223], v[40:43]
	v_mfma_f32_16x16x128_f8f6f4 v[32:35], v[24:31], v[216:223], v[32:35]
	s_setprio 0
	s_barrier
	s_cbranch_scc0 .LBB0_585
	s_nop 15
	s_nop 15
	s_and_b64 vcc, exec, s[8:9]
	s_cbranch_vccz .LBB0_588
	s_barrier

.LBB0_662:
	ds_read_b128 v[24:27], v189
	ds_read_b128 v[28:31], v189 offset:16
	ds_read_b128 v[16:19], v189 offset:2048
	ds_read_b128 v[20:23], v189 offset:2064
	ds_read_b128 v[8:11], v189 offset:16384
	ds_read_b128 v[12:15], v189 offset:16400
	ds_read_b128 v[0:3], v189 offset:18432
	ds_read_b128 v[4:7], v189 offset:18448
	s_add_u32 s24, s20, 0xfffa8080
	s_addc_u32 s25, s21, -1
	s_cmp_eq_u32 s48, 18
	s_cselect_b32 s27, s1, s25
	s_cselect_b32 s26, s0, s24
	s_cselect_b32 s25, s15, s47
	s_cselect_b32 s24, s14, s45
	s_add_i32 m0, s3, 0xc000
	ds_read_b128 v[176:179], v190
	ds_read_b128 v[180:183], v190 offset:16
	ds_read_b128 v[192:195], v190 offset:2048
	ds_read_b128 v[196:199], v190 offset:2064
	ds_read_b128 v[200:203], v190 offset:4096
	ds_read_b128 v[204:207], v190 offset:4112
	ds_read_b128 v[208:211], v190 offset:6144
	ds_read_b128 v[212:215], v190 offset:6160
	global_load_lds_dwordx4 v164, s[20:21]
	s_add_i32 m0, s3, 0xe000
	v_mov_b32_e32 v169, v165
	global_load_lds_dwordx4 v168, s[20:21]
	s_waitcnt vmcnt(8)
	s_waitcnt lgkmcnt(0)
	s_barrier
	s_setprio 1
	s_waitcnt lgkmcnt(0)
	v_mfma_f32_16x16x128_f8f6f4 v[156:159], v[24:31], v[176:183], v[156:159]
	v_mfma_f32_16x16x128_f8f6f4 v[152:155], v[16:23], v[176:183], v[152:155]
	v_mfma_f32_16x16x128_f8f6f4 v[148:151], v[24:31], v[192:199], v[148:151]
	v_mfma_f32_16x16x128_f8f6f4 v[140:143], v[16:23], v[192:199], v[140:143]
	v_mfma_f32_16x16x128_f8f6f4 v[132:135], v[24:31], v[200:207], v[132:135]
	v_mfma_f32_16x16x128_f8f6f4 v[124:127], v[16:23], v[200:207], v[124:127]
	v_mfma_f32_16x16x128_f8f6f4 v[116:119], v[24:31], v[208:215], v[116:119]
	v_mfma_f32_16x16x128_f8f6f4 v[108:111], v[16:23], v[208:215], v[108:111]
	s_setprio 0
	s_setprio 1
	v_mfma_f32_16x16x128_f8f6f4 v[144:147], v[8:15], v[176:183], v[144:147]
	v_mfma_f32_16x16x128_f8f6f4 v[136:139], v[0:7], v[176:183], v[136:139]
	v_mfma_f32_16x16x128_f8f6f4 v[128:131], v[8:15], v[192:199], v[128:131]
	v_mfma_f32_16x16x128_f8f6f4 v[120:123], v[0:7], v[192:199], v[120:123]
	v_mfma_f32_16x16x128_f8f6f4 v[112:115], v[8:15], v[200:207], v[112:115]
	v_mfma_f32_16x16x128_f8f6f4 v[104:107], v[0:7], v[200:207], v[104:107]
	v_mfma_f32_16x16x128_f8f6f4 v[100:103], v[8:15], v[208:215], v[100:103]
	v_mfma_f32_16x16x128_f8f6f4 v[96:99], v[0:7], v[208:215], v[96:99]
	s_setprio 0
	s_barrier
	s_mov_b32 m0, s13
	ds_read_b128 v[192:195], v190 offset:16384
	ds_read_b128 v[196:199], v190 offset:16400
	ds_read_b128 v[200:203], v190 offset:18432
	ds_read_b128 v[204:207], v190 offset:18448
	ds_read_b128 v[208:211], v190 offset:20480
	ds_read_b128 v[212:215], v190 offset:20496
	ds_read_b128 v[216:219], v190 offset:22528
	ds_read_b128 v[220:223], v190 offset:22544
	global_load_lds_dwordx4 v166, s[24:25]
	s_mov_b32 m0, s22
	s_add_u32 s50, s24, 0x58000
	global_load_lds_dwordx4 v170, s[24:25]
	s_addc_u32 s51, s25, 0
	s_mov_b32 m0, s23
	v_mov_b32_e32 v167, v165
	global_load_lds_dwordx4 v166, s[50:51]
	s_mov_b32 m0, s28
	v_mov_b32_e32 v171, v165
	global_load_lds_dwordx4 v170, s[50:51]
	s_waitcnt vmcnt(6)
	s_waitcnt lgkmcnt(0)
	s_barrier
	s_setprio 1
	s_waitcnt lgkmcnt(0)
	v_mfma_f32_16x16x128_f8f6f4 v[92:95], v[24:31], v[192:199], v[92:95]
	v_mfma_f32_16x16x128_f8f6f4 v[88:91], v[16:23], v[192:199], v[88:91]
	s_mov_b32 m0, s3
	v_lshl_add_u64 v[182:183], s[24:25], 0, v[166:167]
	v_mfma_f32_16x16x128_f8f6f4 v[84:87], v[24:31], v[200:207], v[84:87]
	global_load_lds_dwordx4 v164, s[26:27]
	v_mfma_f32_16x16x128_f8f6f4 v[76:79], v[16:23], v[200:207], v[76:79]
	v_mfma_f32_16x16x128_f8f6f4 v[68:71], v[24:31], v[208:215], v[68:71]
	v_mfma_f32_16x16x128_f8f6f4 v[60:63], v[16:23], v[208:215], v[60:63]
	v_mfma_f32_16x16x128_f8f6f4 v[52:55], v[24:31], v[216:223], v[52:55]
	v_mfma_f32_16x16x128_f8f6f4 v[44:47], v[16:23], v[216:223], v[44:47]
	s_mov_b32 m0, s29
	v_lshl_add_u64 v[180:181], s[24:25], 0, v[170:171]
	s_setprio 0
	s_setprio 1
	v_mfma_f32_16x16x128_f8f6f4 v[80:83], v[8:15], v[192:199], v[80:83]
	global_load_lds_dwordx4 v168, s[26:27]
	v_lshl_add_u64 v[178:179], s[26:27], 0, v[164:165]
	v_lshl_add_u64 v[176:177], s[26:27], 0, v[168:169]
	v_mfma_f32_16x16x128_f8f6f4 v[72:75], v[0:7], v[192:199], v[72:75]
	v_mfma_f32_16x16x128_f8f6f4 v[64:67], v[8:15], v[200:207], v[64:67]
	v_mfma_f32_16x16x128_f8f6f4 v[56:59], v[0:7], v[200:207], v[56:59]
	v_mfma_f32_16x16x128_f8f6f4 v[48:51], v[8:15], v[208:215], v[48:51]
	v_mfma_f32_16x16x128_f8f6f4 v[40:43], v[0:7], v[208:215], v[40:43]
	v_mfma_f32_16x16x128_f8f6f4 v[36:39], v[8:15], v[216:223], v[36:39]
	v_mfma_f32_16x16x128_f8f6f4 v[32:35], v[0:7], v[216:223], v[32:35]
	s_setprio 0
	s_barrier
	ds_read_b128 v[0:3], v189 offset:32768
	ds_read_b128 v[4:7], v189 offset:32784
	ds_read_b128 v[8:11], v189 offset:34816
	ds_read_b128 v[12:15], v189 offset:34832
	ds_read_b128 v[16:19], v189 offset:49152
	ds_read_b128 v[20:23], v189 offset:49168
	ds_read_b128 v[24:27], v189 offset:51200
	ds_read_b128 v[28:31], v189 offset:51216
	s_add_u32 s26, s26, 0x58000
	s_addc_u32 s27, s27, 0
	s_mov_b32 m0, s30
	ds_read_b128 v[192:195], v190 offset:32768
	ds_read_b128 v[196:199], v190 offset:32784
	ds_read_b128 v[200:203], v190 offset:34816
	ds_read_b128 v[204:207], v190 offset:34832
	ds_read_b128 v[208:211], v190 offset:36864
	ds_read_b128 v[212:215], v190 offset:36880
	ds_read_b128 v[216:219], v190 offset:38912
	ds_read_b128 v[220:223], v190 offset:38928
	global_load_lds_dwordx4 v164, s[26:27]
	s_mov_b32 m0, s31
	s_nop 0
	global_load_lds_dwordx4 v168, s[26:27]
	s_waitcnt vmcnt(8)
	s_waitcnt lgkmcnt(0)
	s_barrier
	s_setprio 1
	s_waitcnt lgkmcnt(0)
	v_mfma_f32_16x16x128_f8f6f4 v[156:159], v[0:7], v[192:199], v[156:159]
	v_mfma_f32_16x16x128_f8f6f4 v[152:155], v[8:15], v[192:199], v[152:155]
	v_mfma_f32_16x16x128_f8f6f4 v[148:151], v[0:7], v[200:207], v[148:151]
	v_mfma_f32_16x16x128_f8f6f4 v[140:143], v[8:15], v[200:207], v[140:143]
	v_mfma_f32_16x16x128_f8f6f4 v[132:135], v[0:7], v[208:215], v[132:135]
	v_mfma_f32_16x16x128_f8f6f4 v[124:127], v[8:15], v[208:215], v[124:127]
	v_mfma_f32_16x16x128_f8f6f4 v[116:119], v[0:7], v[216:223], v[116:119]
	v_mfma_f32_16x16x128_f8f6f4 v[108:111], v[8:15], v[216:223], v[108:111]
	s_setprio 0
	s_setprio 1
	v_mfma_f32_16x16x128_f8f6f4 v[144:147], v[16:23], v[192:199], v[144:147]
	v_mfma_f32_16x16x128_f8f6f4 v[136:139], v[24:31], v[192:199], v[136:139]
	v_mfma_f32_16x16x128_f8f6f4 v[128:131], v[16:23], v[200:207], v[128:131]
	v_mfma_f32_16x16x128_f8f6f4 v[120:123], v[24:31], v[200:207], v[120:123]
	v_mfma_f32_16x16x128_f8f6f4 v[112:115], v[16:23], v[208:215], v[112:115]
	v_mfma_f32_16x16x128_f8f6f4 v[104:107], v[24:31], v[208:215], v[104:107]
	v_mfma_f32_16x16x128_f8f6f4 v[100:103], v[16:23], v[216:223], v[100:103]
	v_mfma_f32_16x16x128_f8f6f4 v[96:99], v[24:31], v[216:223], v[96:99]
	s_setprio 0
	s_barrier
	s_mov_b32 m0, s35
	v_lshl_add_u64 v[182:183], v[182:183], 0, s[8:9]
	ds_read_b128 v[192:195], v190 offset:49152
	ds_read_b128 v[196:199], v190 offset:49168
	ds_read_b128 v[200:203], v190 offset:51200
	ds_read_b128 v[204:207], v190 offset:51216
	ds_read_b128 v[208:211], v190 offset:53248
	ds_read_b128 v[212:215], v190 offset:53264
	ds_read_b128 v[216:219], v190 offset:55296
	ds_read_b128 v[220:223], v190 offset:55312
	global_load_lds_dwordx4 v[182:183], off
	v_lshl_add_u64 v[180:181], v[180:181], 0, s[8:9]
	s_mov_b32 m0, s36
	s_add_u32 s24, s24, 0x58080
	global_load_lds_dwordx4 v[180:181], off
	s_addc_u32 s25, s25, 0
	s_mov_b32 m0, s39
	v_lshl_add_u64 v[178:179], v[178:179], 0, s[8:9]
	global_load_lds_dwordx4 v166, s[24:25]
	s_mov_b32 m0, s40
	v_lshl_add_u64 v[176:177], v[176:177], 0, s[8:9]
	global_load_lds_dwordx4 v170, s[24:25]
	s_waitcnt vmcnt(6)
	s_waitcnt lgkmcnt(0)
	s_barrier
	s_setprio 1
	s_waitcnt lgkmcnt(0)
	v_mfma_f32_16x16x128_f8f6f4 v[92:95], v[0:7], v[192:199], v[92:95]
	v_mfma_f32_16x16x128_f8f6f4 v[88:91], v[8:15], v[192:199], v[88:91]
	s_mov_b32 m0, s37
	v_mfma_f32_16x16x128_f8f6f4 v[84:87], v[0:7], v[200:207], v[84:87]
	global_load_lds_dwordx4 v[178:179], off
	v_mfma_f32_16x16x128_f8f6f4 v[76:79], v[8:15], v[200:207], v[76:79]
	v_mfma_f32_16x16x128_f8f6f4 v[68:71], v[0:7], v[208:215], v[68:71]
	v_mfma_f32_16x16x128_f8f6f4 v[60:63], v[8:15], v[208:215], v[60:63]
	v_mfma_f32_16x16x128_f8f6f4 v[52:55], v[0:7], v[216:223], v[52:55]
	v_mfma_f32_16x16x128_f8f6f4 v[44:47], v[8:15], v[216:223], v[44:47]
	s_mov_b32 m0, s38
	s_setprio 0
	s_setprio 1
	v_mfma_f32_16x16x128_f8f6f4 v[80:83], v[16:23], v[192:199], v[80:83]
	s_add_i32 s48, s48, 2
	global_load_lds_dwordx4 v[176:177], off
	v_mfma_f32_16x16x128_f8f6f4 v[72:75], v[24:31], v[192:199], v[72:75]
	s_add_u32 s20, s20, 0x100
	v_mfma_f32_16x16x128_f8f6f4 v[64:67], v[16:23], v[200:207], v[64:67]
	s_addc_u32 s21, s21, 0
	v_mfma_f32_16x16x128_f8f6f4 v[56:59], v[24:31], v[200:207], v[56:59]
	s_add_u32 s45, s45, 0x100
	v_mfma_f32_16x16x128_f8f6f4 v[48:51], v[16:23], v[208:215], v[48:51]
	s_addc_u32 s47, s47, 0
	v_mfma_f32_16x16x128_f8f6f4 v[40:43], v[24:31], v[208:215], v[40:43]
	s_cmp_gt_u32 s48, 19
	v_mfma_f32_16x16x128_f8f6f4 v[36:39], v[16:23], v[216:223], v[36:39]
	v_mfma_f32_16x16x128_f8f6f4 v[32:35], v[24:31], v[216:223], v[32:35]
	s_setprio 0
	s_barrier
	s_cbranch_scc0 .LBB0_662
	s_nop 15
	s_nop 15
	s_and_b64 vcc, exec, s[10:11]
	s_cbranch_vccz .LBB0_665
	s_barrier

.LBB0_792:
	ds_read_b128 v[144:147], v142
	ds_read_b128 v[148:151], v142 offset:1024
	ds_read_b128 v[152:155], v142 offset:2048
	ds_read_b128 v[156:159], v142 offset:3072
	ds_read_b128 v[164:167], v142 offset:16384
	ds_read_b128 v[168:171], v142 offset:17408
	ds_read_b128 v[172:175], v142 offset:18432
	ds_read_b128 v[176:179], v142 offset:19456
	s_add_u32 s26, s24, 0xfffc0080
	s_addc_u32 s27, s25, -1
	s_cmp_eq_u32 s49, 12
	s_cselect_b32 s29, s13, s27
	s_cselect_b32 s28, s44, s26
	s_cselect_b32 s27, s11, s48
	s_cselect_b32 s26, s45, s47
	s_add_i32 m0, s3, 0xc000
	ds_read_b128 v[180:183], v143
	ds_read_b128 v[188:191], v143 offset:1024
	ds_read_b128 v[192:195], v143 offset:2048
	ds_read_b128 v[196:199], v143 offset:3072
	ds_read_b128 v[200:203], v143 offset:4096
	ds_read_b128 v[204:207], v143 offset:5120
	ds_read_b128 v[208:211], v143 offset:6144
	ds_read_b128 v[212:215], v143 offset:7168
	global_load_lds_dwordx4 v128, s[24:25]
	s_add_i32 m0, s3, 0xe000
	v_mov_b32_e32 v131, v129
	global_load_lds_dwordx4 v130, s[24:25]
	s_waitcnt vmcnt(8)
	s_waitcnt lgkmcnt(0)
	s_barrier
	s_setprio 1
	s_waitcnt lgkmcnt(0)
	v_mfma_f32_16x16x32_bf16 v[124:127], v[144:147], v[180:183], v[124:127]
	v_mfma_f32_16x16x32_bf16 v[120:123], v[152:155], v[180:183], v[120:123]
	v_mfma_f32_16x16x32_bf16 v[116:119], v[144:147], v[192:195], v[116:119]
	v_mfma_f32_16x16x32_bf16 v[112:115], v[152:155], v[192:195], v[112:115]
	v_mfma_f32_16x16x32_bf16 v[100:103], v[144:147], v[200:203], v[100:103]
	v_mfma_f32_16x16x32_bf16 v[96:99], v[152:155], v[200:203], v[96:99]
	v_mfma_f32_16x16x32_bf16 v[84:87], v[144:147], v[208:211], v[84:87]
	v_mfma_f32_16x16x32_bf16 v[80:83], v[152:155], v[208:211], v[80:83]
	v_mfma_f32_16x16x32_bf16 v[124:127], v[148:151], v[188:191], v[124:127]
	v_mfma_f32_16x16x32_bf16 v[120:123], v[156:159], v[188:191], v[120:123]
	v_mfma_f32_16x16x32_bf16 v[116:119], v[148:151], v[196:199], v[116:119]
	v_mfma_f32_16x16x32_bf16 v[112:115], v[156:159], v[196:199], v[112:115]
	v_mfma_f32_16x16x32_bf16 v[100:103], v[148:151], v[204:207], v[100:103]
	v_mfma_f32_16x16x32_bf16 v[96:99], v[156:159], v[204:207], v[96:99]
	v_mfma_f32_16x16x32_bf16 v[84:87], v[148:151], v[212:215], v[84:87]
	v_mfma_f32_16x16x32_bf16 v[80:83], v[156:159], v[212:215], v[80:83]
	s_setprio 0
	s_setprio 1
	v_mfma_f32_16x16x32_bf16 v[108:111], v[164:167], v[180:183], v[108:111]
	v_mfma_f32_16x16x32_bf16 v[104:107], v[172:175], v[180:183], v[104:107]
	v_mfma_f32_16x16x32_bf16 v[92:95], v[164:167], v[192:195], v[92:95]
	v_mfma_f32_16x16x32_bf16 v[88:91], v[172:175], v[192:195], v[88:91]
	v_mfma_f32_16x16x32_bf16 v[76:79], v[164:167], v[200:203], v[76:79]
	v_mfma_f32_16x16x32_bf16 v[72:75], v[172:175], v[200:203], v[72:75]
	v_mfma_f32_16x16x32_bf16 v[68:71], v[164:167], v[208:211], v[68:71]
	v_mfma_f32_16x16x32_bf16 v[64:67], v[172:175], v[208:211], v[64:67]
	v_mfma_f32_16x16x32_bf16 v[108:111], v[168:171], v[188:191], v[108:111]
	v_mfma_f32_16x16x32_bf16 v[104:107], v[176:179], v[188:191], v[104:107]
	v_mfma_f32_16x16x32_bf16 v[92:95], v[168:171], v[196:199], v[92:95]
	v_mfma_f32_16x16x32_bf16 v[88:91], v[176:179], v[196:199], v[88:91]
	v_mfma_f32_16x16x32_bf16 v[76:79], v[168:171], v[204:207], v[76:79]
	v_mfma_f32_16x16x32_bf16 v[72:75], v[176:179], v[204:207], v[72:75]
	v_mfma_f32_16x16x32_bf16 v[68:71], v[168:171], v[212:215], v[68:71]
	v_mfma_f32_16x16x32_bf16 v[64:67], v[176:179], v[212:215], v[64:67]
	s_setprio 0
	s_barrier
	s_mov_b32 m0, s15
	ds_read_b128 v[180:183], v143 offset:16384
	ds_read_b128 v[188:191], v143 offset:17408
	ds_read_b128 v[192:195], v143 offset:18432
	ds_read_b128 v[196:199], v143 offset:19456
	ds_read_b128 v[200:203], v143 offset:20480
	ds_read_b128 v[204:207], v143 offset:21504
	ds_read_b128 v[208:211], v143 offset:22528
	ds_read_b128 v[212:215], v143 offset:23552
	global_load_lds_dwordx4 v138, s[26:27]
	s_mov_b32 m0, s22
	s_add_u32 s50, s26, 0x40000
	global_load_lds_dwordx4 v132, s[26:27]
	s_addc_u32 s51, s27, 0
	s_mov_b32 m0, s23
	v_mov_b32_e32 v139, v129
	global_load_lds_dwordx4 v138, s[50:51]
	s_mov_b32 m0, s30
	v_mov_b32_e32 v133, v129
	global_load_lds_dwordx4 v132, s[50:51]
	s_waitcnt vmcnt(6)
	s_waitcnt lgkmcnt(0)
	s_barrier
	s_setprio 1
	s_waitcnt lgkmcnt(0)
	v_mfma_f32_16x16x32_bf16 v[60:63], v[144:147], v[180:183], v[60:63]
	v_mfma_f32_16x16x32_bf16 v[56:59], v[152:155], v[180:183], v[56:59]
	s_mov_b32 m0, s3
	v_lshl_add_u64 v[216:217], s[26:27], 0, v[138:139]
	v_mfma_f32_16x16x32_bf16 v[52:55], v[144:147], v[192:195], v[52:55]
	global_load_lds_dwordx4 v128, s[28:29]
	v_mfma_f32_16x16x32_bf16 v[48:51], v[152:155], v[192:195], v[48:51]
	v_mfma_f32_16x16x32_bf16 v[36:39], v[144:147], v[200:203], v[36:39]
	v_mfma_f32_16x16x32_bf16 v[32:35], v[152:155], v[200:203], v[32:35]
	v_mfma_f32_16x16x32_bf16 v[20:23], v[144:147], v[208:211], v[20:23]
	v_mfma_f32_16x16x32_bf16 v[16:19], v[152:155], v[208:211], v[16:19]
	v_mfma_f32_16x16x32_bf16 v[60:63], v[148:151], v[188:191], v[60:63]
	v_mfma_f32_16x16x32_bf16 v[56:59], v[156:159], v[188:191], v[56:59]
	v_mfma_f32_16x16x32_bf16 v[52:55], v[148:151], v[196:199], v[52:55]
	v_mfma_f32_16x16x32_bf16 v[48:51], v[156:159], v[196:199], v[48:51]
	v_mfma_f32_16x16x32_bf16 v[36:39], v[148:151], v[204:207], v[36:39]
	v_mfma_f32_16x16x32_bf16 v[32:35], v[156:159], v[204:207], v[32:35]
	v_mfma_f32_16x16x32_bf16 v[20:23], v[148:151], v[212:215], v[20:23]
	v_mfma_f32_16x16x32_bf16 v[16:19], v[156:159], v[212:215], v[16:19]
	s_mov_b32 m0, s31
	v_lshl_add_u64 v[218:219], s[26:27], 0, v[132:133]
	s_setprio 0
	s_setprio 1
	v_mfma_f32_16x16x32_bf16 v[44:47], v[164:167], v[180:183], v[44:47]
	global_load_lds_dwordx4 v130, s[28:29]
	v_lshl_add_u64 v[220:221], s[28:29], 0, v[128:129]
	v_lshl_add_u64 v[222:223], s[28:29], 0, v[130:131]
	v_mfma_f32_16x16x32_bf16 v[40:43], v[172:175], v[180:183], v[40:43]
	v_mfma_f32_16x16x32_bf16 v[28:31], v[164:167], v[192:195], v[28:31]
	v_mfma_f32_16x16x32_bf16 v[24:27], v[172:175], v[192:195], v[24:27]
	v_mfma_f32_16x16x32_bf16 v[12:15], v[164:167], v[200:203], v[12:15]
	v_mfma_f32_16x16x32_bf16 v[8:11], v[172:175], v[200:203], v[8:11]
	v_mfma_f32_16x16x32_bf16 v[4:7], v[164:167], v[208:211], v[4:7]
	v_mfma_f32_16x16x32_bf16 v[0:3], v[172:175], v[208:211], v[0:3]
	v_mfma_f32_16x16x32_bf16 v[44:47], v[168:171], v[188:191], v[44:47]
	v_mfma_f32_16x16x32_bf16 v[40:43], v[176:179], v[188:191], v[40:43]
	v_mfma_f32_16x16x32_bf16 v[28:31], v[168:171], v[196:199], v[28:31]
	v_mfma_f32_16x16x32_bf16 v[24:27], v[176:179], v[196:199], v[24:27]
	v_mfma_f32_16x16x32_bf16 v[12:15], v[168:171], v[204:207], v[12:15]
	v_mfma_f32_16x16x32_bf16 v[8:11], v[176:179], v[204:207], v[8:11]
	v_mfma_f32_16x16x32_bf16 v[4:7], v[168:171], v[212:215], v[4:7]
	v_mfma_f32_16x16x32_bf16 v[0:3], v[176:179], v[212:215], v[0:3]
	s_setprio 0
	s_barrier
	ds_read_b128 v[144:147], v142 offset:32768
	ds_read_b128 v[148:151], v142 offset:33792
	ds_read_b128 v[152:155], v142 offset:34816
	ds_read_b128 v[156:159], v142 offset:35840
	ds_read_b128 v[164:167], v142 offset:49152
	ds_read_b128 v[168:171], v142 offset:50176
	ds_read_b128 v[172:175], v142 offset:51200
	ds_read_b128 v[176:179], v142 offset:52224
	s_add_u32 s28, s28, 0x40000
	s_addc_u32 s29, s29, 0
	s_mov_b32 m0, s34
	ds_read_b128 v[180:183], v143 offset:32768
	ds_read_b128 v[188:191], v143 offset:33792
	ds_read_b128 v[192:195], v143 offset:34816
	ds_read_b128 v[196:199], v143 offset:35840
	ds_read_b128 v[200:203], v143 offset:36864
	ds_read_b128 v[204:207], v143 offset:37888
	ds_read_b128 v[208:211], v143 offset:38912
	ds_read_b128 v[212:215], v143 offset:39936
	global_load_lds_dwordx4 v128, s[28:29]
	s_mov_b32 m0, s35
	s_nop 0
	global_load_lds_dwordx4 v130, s[28:29]
	s_waitcnt vmcnt(8)
	s_waitcnt lgkmcnt(0)
	s_barrier
	s_setprio 1
	s_waitcnt lgkmcnt(0)
	v_mfma_f32_16x16x32_bf16 v[124:127], v[144:147], v[180:183], v[124:127]
	v_mfma_f32_16x16x32_bf16 v[120:123], v[152:155], v[180:183], v[120:123]
	v_mfma_f32_16x16x32_bf16 v[116:119], v[144:147], v[192:195], v[116:119]
	v_mfma_f32_16x16x32_bf16 v[112:115], v[152:155], v[192:195], v[112:115]
	v_mfma_f32_16x16x32_bf16 v[100:103], v[144:147], v[200:203], v[100:103]
	v_mfma_f32_16x16x32_bf16 v[96:99], v[152:155], v[200:203], v[96:99]
	v_mfma_f32_16x16x32_bf16 v[84:87], v[144:147], v[208:211], v[84:87]
	v_mfma_f32_16x16x32_bf16 v[80:83], v[152:155], v[208:211], v[80:83]
	v_mfma_f32_16x16x32_bf16 v[124:127], v[148:151], v[188:191], v[124:127]
	v_mfma_f32_16x16x32_bf16 v[120:123], v[156:159], v[188:191], v[120:123]
	v_mfma_f32_16x16x32_bf16 v[116:119], v[148:151], v[196:199], v[116:119]
	v_mfma_f32_16x16x32_bf16 v[112:115], v[156:159], v[196:199], v[112:115]
	v_mfma_f32_16x16x32_bf16 v[100:103], v[148:151], v[204:207], v[100:103]
	v_mfma_f32_16x16x32_bf16 v[96:99], v[156:159], v[204:207], v[96:99]
	v_mfma_f32_16x16x32_bf16 v[84:87], v[148:151], v[212:215], v[84:87]
	v_mfma_f32_16x16x32_bf16 v[80:83], v[156:159], v[212:215], v[80:83]
	s_setprio 0
	s_setprio 1
	v_mfma_f32_16x16x32_bf16 v[108:111], v[164:167], v[180:183], v[108:111]
	v_mfma_f32_16x16x32_bf16 v[104:107], v[172:175], v[180:183], v[104:107]
	v_mfma_f32_16x16x32_bf16 v[92:95], v[164:167], v[192:195], v[92:95]
	v_mfma_f32_16x16x32_bf16 v[88:91], v[172:175], v[192:195], v[88:91]
	v_mfma_f32_16x16x32_bf16 v[76:79], v[164:167], v[200:203], v[76:79]
	v_mfma_f32_16x16x32_bf16 v[72:75], v[172:175], v[200:203], v[72:75]
	v_mfma_f32_16x16x32_bf16 v[68:71], v[164:167], v[208:211], v[68:71]
	v_mfma_f32_16x16x32_bf16 v[64:67], v[172:175], v[208:211], v[64:67]
	v_mfma_f32_16x16x32_bf16 v[108:111], v[168:171], v[188:191], v[108:111]
	v_mfma_f32_16x16x32_bf16 v[104:107], v[176:179], v[188:191], v[104:107]
	v_mfma_f32_16x16x32_bf16 v[92:95], v[168:171], v[196:199], v[92:95]
	v_mfma_f32_16x16x32_bf16 v[88:91], v[176:179], v[196:199], v[88:91]
	v_mfma_f32_16x16x32_bf16 v[76:79], v[168:171], v[204:207], v[76:79]
	v_mfma_f32_16x16x32_bf16 v[72:75], v[176:179], v[204:207], v[72:75]
	v_mfma_f32_16x16x32_bf16 v[68:71], v[168:171], v[212:215], v[68:71]
	v_mfma_f32_16x16x32_bf16 v[64:67], v[176:179], v[212:215], v[64:67]
	s_setprio 0
	s_barrier
	s_mov_b32 m0, s37
	v_lshl_add_u64 v[216:217], v[216:217], 0, s[6:7]
	ds_read_b128 v[180:183], v143 offset:49152
	ds_read_b128 v[188:191], v143 offset:50176
	ds_read_b128 v[192:195], v143 offset:51200
	ds_read_b128 v[196:199], v143 offset:52224
	ds_read_b128 v[200:203], v143 offset:53248
	ds_read_b128 v[204:207], v143 offset:54272
	ds_read_b128 v[208:211], v143 offset:55296
	ds_read_b128 v[212:215], v143 offset:56320
	global_load_lds_dwordx4 v[216:217], off
	v_lshl_add_u64 v[216:217], v[218:219], 0, s[6:7]
	s_mov_b32 m0, s38
	s_add_u32 s26, s26, 0x40080
	global_load_lds_dwordx4 v[216:217], off
	s_addc_u32 s27, s27, 0
	s_mov_b32 m0, s41
	v_lshl_add_u64 v[216:217], v[220:221], 0, s[6:7]
	global_load_lds_dwordx4 v138, s[26:27]
	s_mov_b32 m0, s42
	s_nop 0
	global_load_lds_dwordx4 v132, s[26:27]
	s_waitcnt vmcnt(6)
	s_waitcnt lgkmcnt(0)
	s_barrier
	s_setprio 1
	s_waitcnt lgkmcnt(0)
	v_mfma_f32_16x16x32_bf16 v[60:63], v[144:147], v[180:183], v[60:63]
	v_mfma_f32_16x16x32_bf16 v[56:59], v[152:155], v[180:183], v[56:59]
	s_mov_b32 m0, s39
	v_mfma_f32_16x16x32_bf16 v[52:55], v[144:147], v[192:195], v[52:55]
	global_load_lds_dwordx4 v[216:217], off
	v_mfma_f32_16x16x32_bf16 v[48:51], v[152:155], v[192:195], v[48:51]
	v_mfma_f32_16x16x32_bf16 v[36:39], v[144:147], v[200:203], v[36:39]
	v_mfma_f32_16x16x32_bf16 v[32:35], v[152:155], v[200:203], v[32:35]
	v_mfma_f32_16x16x32_bf16 v[20:23], v[144:147], v[208:211], v[20:23]
	v_mfma_f32_16x16x32_bf16 v[16:19], v[152:155], v[208:211], v[16:19]
	v_mfma_f32_16x16x32_bf16 v[60:63], v[148:151], v[188:191], v[60:63]
	v_mfma_f32_16x16x32_bf16 v[56:59], v[156:159], v[188:191], v[56:59]
	v_mfma_f32_16x16x32_bf16 v[52:55], v[148:151], v[196:199], v[52:55]
	v_mfma_f32_16x16x32_bf16 v[48:51], v[156:159], v[196:199], v[48:51]
	v_mfma_f32_16x16x32_bf16 v[36:39], v[148:151], v[204:207], v[36:39]
	v_mfma_f32_16x16x32_bf16 v[32:35], v[156:159], v[204:207], v[32:35]
	v_mfma_f32_16x16x32_bf16 v[20:23], v[148:151], v[212:215], v[20:23]
	v_mfma_f32_16x16x32_bf16 v[16:19], v[156:159], v[212:215], v[16:19]
	v_lshl_add_u64 v[216:217], v[222:223], 0, s[6:7]
	s_mov_b32 m0, s40
	s_setprio 0
	s_setprio 1
	v_mfma_f32_16x16x32_bf16 v[44:47], v[164:167], v[180:183], v[44:47]
	global_load_lds_dwordx4 v[216:217], off
	v_mfma_f32_16x16x32_bf16 v[40:43], v[172:175], v[180:183], v[40:43]
	v_mfma_f32_16x16x32_bf16 v[28:31], v[164:167], v[192:195], v[28:31]
	v_mfma_f32_16x16x32_bf16 v[24:27], v[172:175], v[192:195], v[24:27]
	v_mfma_f32_16x16x32_bf16 v[12:15], v[164:167], v[200:203], v[12:15]
	v_mfma_f32_16x16x32_bf16 v[8:11], v[172:175], v[200:203], v[8:11]
	v_mfma_f32_16x16x32_bf16 v[4:7], v[164:167], v[208:211], v[4:7]
	v_mfma_f32_16x16x32_bf16 v[0:3], v[172:175], v[208:211], v[0:3]
	v_mfma_f32_16x16x32_bf16 v[44:47], v[168:171], v[188:191], v[44:47]
	s_add_i32 s49, s49, 2
	v_mfma_f32_16x16x32_bf16 v[40:43], v[176:179], v[188:191], v[40:43]
	s_add_u32 s24, s24, 0x100
	v_mfma_f32_16x16x32_bf16 v[28:31], v[168:171], v[196:199], v[28:31]
	s_addc_u32 s25, s25, 0
	v_mfma_f32_16x16x32_bf16 v[24:27], v[176:179], v[196:199], v[24:27]
	s_add_u32 s47, s47, 0x100
	v_mfma_f32_16x16x32_bf16 v[12:15], v[168:171], v[204:207], v[12:15]
	s_addc_u32 s48, s48, 0
	v_mfma_f32_16x16x32_bf16 v[8:11], v[176:179], v[204:207], v[8:11]
	s_cmp_gt_u32 s49, 13
	v_mfma_f32_16x16x32_bf16 v[4:7], v[168:171], v[212:215], v[4:7]
	v_mfma_f32_16x16x32_bf16 v[0:3], v[176:179], v[212:215], v[0:3]
	s_setprio 0
	s_barrier
	s_cbranch_scc0 .LBB0_792
	s_and_b64 vcc, exec, s[8:9]
	s_cbranch_vccz .LBB0_795
	s_barrier

.LBB0_993:
	ds_read_b128 v[144:147], v142
	ds_read_b128 v[148:151], v142 offset:1024
	ds_read_b128 v[152:155], v142 offset:2048
	ds_read_b128 v[156:159], v142 offset:3072
	ds_read_b128 v[164:167], v142 offset:16384
	ds_read_b128 v[168:171], v142 offset:17408
	ds_read_b128 v[172:175], v142 offset:18432
	ds_read_b128 v[176:179], v142 offset:19456
	s_add_u32 s28, s26, 0xfffc0080
	s_addc_u32 s29, s27, -1
	s_cmp_eq_u32 s54, 12
	s_cselect_b32 s31, s17, s29
	s_cselect_b32 s30, s50, s28
	s_cselect_b32 s29, s15, s53
	s_cselect_b32 s28, s51, s52
	s_add_i32 m0, s3, 0xc000
	ds_read_b128 v[180:183], v143
	ds_read_b128 v[188:191], v143 offset:1024
	ds_read_b128 v[192:195], v143 offset:2048
	ds_read_b128 v[196:199], v143 offset:3072
	ds_read_b128 v[200:203], v143 offset:4096
	ds_read_b128 v[204:207], v143 offset:5120
	ds_read_b128 v[208:211], v143 offset:6144
	ds_read_b128 v[212:215], v143 offset:7168
	global_load_lds_dwordx4 v128, s[26:27]
	s_add_i32 m0, s3, 0xe000
	v_mov_b32_e32 v131, v129
	global_load_lds_dwordx4 v130, s[26:27]
	s_waitcnt vmcnt(8)
	s_waitcnt lgkmcnt(0)
	s_barrier
	s_setprio 1
	s_waitcnt lgkmcnt(0)
	v_mfma_f32_16x16x32_bf16 v[124:127], v[144:147], v[180:183], v[124:127]
	v_mfma_f32_16x16x32_bf16 v[120:123], v[152:155], v[180:183], v[120:123]
	v_mfma_f32_16x16x32_bf16 v[116:119], v[144:147], v[192:195], v[116:119]
	v_mfma_f32_16x16x32_bf16 v[112:115], v[152:155], v[192:195], v[112:115]
	v_mfma_f32_16x16x32_bf16 v[100:103], v[144:147], v[200:203], v[100:103]
	v_mfma_f32_16x16x32_bf16 v[96:99], v[152:155], v[200:203], v[96:99]
	v_mfma_f32_16x16x32_bf16 v[84:87], v[144:147], v[208:211], v[84:87]
	v_mfma_f32_16x16x32_bf16 v[80:83], v[152:155], v[208:211], v[80:83]
	v_mfma_f32_16x16x32_bf16 v[124:127], v[148:151], v[188:191], v[124:127]
	v_mfma_f32_16x16x32_bf16 v[120:123], v[156:159], v[188:191], v[120:123]
	v_mfma_f32_16x16x32_bf16 v[116:119], v[148:151], v[196:199], v[116:119]
	v_mfma_f32_16x16x32_bf16 v[112:115], v[156:159], v[196:199], v[112:115]
	v_mfma_f32_16x16x32_bf16 v[100:103], v[148:151], v[204:207], v[100:103]
	v_mfma_f32_16x16x32_bf16 v[96:99], v[156:159], v[204:207], v[96:99]
	v_mfma_f32_16x16x32_bf16 v[84:87], v[148:151], v[212:215], v[84:87]
	v_mfma_f32_16x16x32_bf16 v[80:83], v[156:159], v[212:215], v[80:83]
	s_setprio 0
	s_setprio 1
	v_mfma_f32_16x16x32_bf16 v[108:111], v[164:167], v[180:183], v[108:111]
	v_mfma_f32_16x16x32_bf16 v[104:107], v[172:175], v[180:183], v[104:107]
	v_mfma_f32_16x16x32_bf16 v[92:95], v[164:167], v[192:195], v[92:95]
	v_mfma_f32_16x16x32_bf16 v[88:91], v[172:175], v[192:195], v[88:91]
	v_mfma_f32_16x16x32_bf16 v[76:79], v[164:167], v[200:203], v[76:79]
	v_mfma_f32_16x16x32_bf16 v[72:75], v[172:175], v[200:203], v[72:75]
	v_mfma_f32_16x16x32_bf16 v[68:71], v[164:167], v[208:211], v[68:71]
	v_mfma_f32_16x16x32_bf16 v[64:67], v[172:175], v[208:211], v[64:67]
	v_mfma_f32_16x16x32_bf16 v[108:111], v[168:171], v[188:191], v[108:111]
	v_mfma_f32_16x16x32_bf16 v[104:107], v[176:179], v[188:191], v[104:107]
	v_mfma_f32_16x16x32_bf16 v[92:95], v[168:171], v[196:199], v[92:95]
	v_mfma_f32_16x16x32_bf16 v[88:91], v[176:179], v[196:199], v[88:91]
	v_mfma_f32_16x16x32_bf16 v[76:79], v[168:171], v[204:207], v[76:79]
	v_mfma_f32_16x16x32_bf16 v[72:75], v[176:179], v[204:207], v[72:75]
	v_mfma_f32_16x16x32_bf16 v[68:71], v[168:171], v[212:215], v[68:71]
	v_mfma_f32_16x16x32_bf16 v[64:67], v[176:179], v[212:215], v[64:67]
	s_setprio 0
	s_barrier
	s_mov_b32 m0, s19
	ds_read_b128 v[180:183], v143 offset:16384
	ds_read_b128 v[188:191], v143 offset:17408
	ds_read_b128 v[192:195], v143 offset:18432
	ds_read_b128 v[196:199], v143 offset:19456
	ds_read_b128 v[200:203], v143 offset:20480
	ds_read_b128 v[204:207], v143 offset:21504
	ds_read_b128 v[208:211], v143 offset:22528
	ds_read_b128 v[212:215], v143 offset:23552
	global_load_lds_dwordx4 v138, s[28:29]
	s_mov_b32 m0, s22
	s_add_u32 s62, s28, 0x40000
	global_load_lds_dwordx4 v132, s[28:29]
	s_addc_u32 s63, s29, 0
	s_mov_b32 m0, s23
	v_mov_b32_e32 v139, v129
	global_load_lds_dwordx4 v138, s[62:63]
	s_mov_b32 m0, s34
	v_mov_b32_e32 v133, v129
	global_load_lds_dwordx4 v132, s[62:63]
	s_waitcnt vmcnt(6)
	s_waitcnt lgkmcnt(0)
	s_barrier
	s_setprio 1
	s_waitcnt lgkmcnt(0)
	v_mfma_f32_16x16x32_bf16 v[60:63], v[144:147], v[180:183], v[60:63]
	v_mfma_f32_16x16x32_bf16 v[56:59], v[152:155], v[180:183], v[56:59]
	s_mov_b32 m0, s3
	v_lshl_add_u64 v[216:217], s[28:29], 0, v[138:139]
	v_mfma_f32_16x16x32_bf16 v[52:55], v[144:147], v[192:195], v[52:55]
	global_load_lds_dwordx4 v128, s[30:31]
	v_mfma_f32_16x16x32_bf16 v[48:51], v[152:155], v[192:195], v[48:51]
	v_mfma_f32_16x16x32_bf16 v[36:39], v[144:147], v[200:203], v[36:39]
	v_mfma_f32_16x16x32_bf16 v[32:35], v[152:155], v[200:203], v[32:35]
	v_mfma_f32_16x16x32_bf16 v[20:23], v[144:147], v[208:211], v[20:23]
	v_mfma_f32_16x16x32_bf16 v[16:19], v[152:155], v[208:211], v[16:19]
	v_mfma_f32_16x16x32_bf16 v[60:63], v[148:151], v[188:191], v[60:63]
	v_mfma_f32_16x16x32_bf16 v[56:59], v[156:159], v[188:191], v[56:59]
	v_mfma_f32_16x16x32_bf16 v[52:55], v[148:151], v[196:199], v[52:55]
	v_mfma_f32_16x16x32_bf16 v[48:51], v[156:159], v[196:199], v[48:51]
	v_mfma_f32_16x16x32_bf16 v[36:39], v[148:151], v[204:207], v[36:39]
	v_mfma_f32_16x16x32_bf16 v[32:35], v[156:159], v[204:207], v[32:35]
	v_mfma_f32_16x16x32_bf16 v[20:23], v[148:151], v[212:215], v[20:23]
	v_mfma_f32_16x16x32_bf16 v[16:19], v[156:159], v[212:215], v[16:19]
	s_mov_b32 m0, s35
	v_lshl_add_u64 v[218:219], s[28:29], 0, v[132:133]
	s_setprio 0
	s_setprio 1
	v_mfma_f32_16x16x32_bf16 v[44:47], v[164:167], v[180:183], v[44:47]
	global_load_lds_dwordx4 v130, s[30:31]
	v_lshl_add_u64 v[220:221], s[30:31], 0, v[128:129]
	v_lshl_add_u64 v[222:223], s[30:31], 0, v[130:131]
	v_mfma_f32_16x16x32_bf16 v[40:43], v[172:175], v[180:183], v[40:43]
	v_mfma_f32_16x16x32_bf16 v[28:31], v[164:167], v[192:195], v[28:31]
	v_mfma_f32_16x16x32_bf16 v[24:27], v[172:175], v[192:195], v[24:27]
	v_mfma_f32_16x16x32_bf16 v[12:15], v[164:167], v[200:203], v[12:15]
	v_mfma_f32_16x16x32_bf16 v[8:11], v[172:175], v[200:203], v[8:11]
	v_mfma_f32_16x16x32_bf16 v[4:7], v[164:167], v[208:211], v[4:7]
	v_mfma_f32_16x16x32_bf16 v[0:3], v[172:175], v[208:211], v[0:3]
	v_mfma_f32_16x16x32_bf16 v[44:47], v[168:171], v[188:191], v[44:47]
	v_mfma_f32_16x16x32_bf16 v[40:43], v[176:179], v[188:191], v[40:43]
	v_mfma_f32_16x16x32_bf16 v[28:31], v[168:171], v[196:199], v[28:31]
	v_mfma_f32_16x16x32_bf16 v[24:27], v[176:179], v[196:199], v[24:27]
	v_mfma_f32_16x16x32_bf16 v[12:15], v[168:171], v[204:207], v[12:15]
	v_mfma_f32_16x16x32_bf16 v[8:11], v[176:179], v[204:207], v[8:11]
	v_mfma_f32_16x16x32_bf16 v[4:7], v[168:171], v[212:215], v[4:7]
	v_mfma_f32_16x16x32_bf16 v[0:3], v[176:179], v[212:215], v[0:3]
	s_setprio 0
	s_barrier
	ds_read_b128 v[144:147], v142 offset:32768
	ds_read_b128 v[148:151], v142 offset:33792
	ds_read_b128 v[152:155], v142 offset:34816
	ds_read_b128 v[156:159], v142 offset:35840
	ds_read_b128 v[164:167], v142 offset:49152
	ds_read_b128 v[168:171], v142 offset:50176
	ds_read_b128 v[172:175], v142 offset:51200
	ds_read_b128 v[176:179], v142 offset:52224
	s_add_u32 s30, s30, 0x40000
	s_addc_u32 s31, s31, 0
	s_mov_b32 m0, s36
	ds_read_b128 v[180:183], v143 offset:32768
	ds_read_b128 v[188:191], v143 offset:33792
	ds_read_b128 v[192:195], v143 offset:34816
	ds_read_b128 v[196:199], v143 offset:35840
	ds_read_b128 v[200:203], v143 offset:36864
	ds_read_b128 v[204:207], v143 offset:37888
	ds_read_b128 v[208:211], v143 offset:38912
	ds_read_b128 v[212:215], v143 offset:39936
	global_load_lds_dwordx4 v128, s[30:31]
	s_mov_b32 m0, s37
	s_nop 0
	global_load_lds_dwordx4 v130, s[30:31]
	s_waitcnt vmcnt(8)
	s_waitcnt lgkmcnt(0)
	s_barrier
	s_setprio 1
	s_waitcnt lgkmcnt(0)
	v_mfma_f32_16x16x32_bf16 v[124:127], v[144:147], v[180:183], v[124:127]
	v_mfma_f32_16x16x32_bf16 v[120:123], v[152:155], v[180:183], v[120:123]
	v_mfma_f32_16x16x32_bf16 v[116:119], v[144:147], v[192:195], v[116:119]
	v_mfma_f32_16x16x32_bf16 v[112:115], v[152:155], v[192:195], v[112:115]
	v_mfma_f32_16x16x32_bf16 v[100:103], v[144:147], v[200:203], v[100:103]
	v_mfma_f32_16x16x32_bf16 v[96:99], v[152:155], v[200:203], v[96:99]
	v_mfma_f32_16x16x32_bf16 v[84:87], v[144:147], v[208:211], v[84:87]
	v_mfma_f32_16x16x32_bf16 v[80:83], v[152:155], v[208:211], v[80:83]
	v_mfma_f32_16x16x32_bf16 v[124:127], v[148:151], v[188:191], v[124:127]
	v_mfma_f32_16x16x32_bf16 v[120:123], v[156:159], v[188:191], v[120:123]
	v_mfma_f32_16x16x32_bf16 v[116:119], v[148:151], v[196:199], v[116:119]
	v_mfma_f32_16x16x32_bf16 v[112:115], v[156:159], v[196:199], v[112:115]
	v_mfma_f32_16x16x32_bf16 v[100:103], v[148:151], v[204:207], v[100:103]
	v_mfma_f32_16x16x32_bf16 v[96:99], v[156:159], v[204:207], v[96:99]
	v_mfma_f32_16x16x32_bf16 v[84:87], v[148:151], v[212:215], v[84:87]
	v_mfma_f32_16x16x32_bf16 v[80:83], v[156:159], v[212:215], v[80:83]
	s_setprio 0
	s_setprio 1
	v_mfma_f32_16x16x32_bf16 v[108:111], v[164:167], v[180:183], v[108:111]
	v_mfma_f32_16x16x32_bf16 v[104:107], v[172:175], v[180:183], v[104:107]
	v_mfma_f32_16x16x32_bf16 v[92:95], v[164:167], v[192:195], v[92:95]
	v_mfma_f32_16x16x32_bf16 v[88:91], v[172:175], v[192:195], v[88:91]
	v_mfma_f32_16x16x32_bf16 v[76:79], v[164:167], v[200:203], v[76:79]
	v_mfma_f32_16x16x32_bf16 v[72:75], v[172:175], v[200:203], v[72:75]
	v_mfma_f32_16x16x32_bf16 v[68:71], v[164:167], v[208:211], v[68:71]
	v_mfma_f32_16x16x32_bf16 v[64:67], v[172:175], v[208:211], v[64:67]
	v_mfma_f32_16x16x32_bf16 v[108:111], v[168:171], v[188:191], v[108:111]
	v_mfma_f32_16x16x32_bf16 v[104:107], v[176:179], v[188:191], v[104:107]
	v_mfma_f32_16x16x32_bf16 v[92:95], v[168:171], v[196:199], v[92:95]
	v_mfma_f32_16x16x32_bf16 v[88:91], v[176:179], v[196:199], v[88:91]
	v_mfma_f32_16x16x32_bf16 v[76:79], v[168:171], v[204:207], v[76:79]
	v_mfma_f32_16x16x32_bf16 v[72:75], v[176:179], v[204:207], v[72:75]
	v_mfma_f32_16x16x32_bf16 v[68:71], v[168:171], v[212:215], v[68:71]
	v_mfma_f32_16x16x32_bf16 v[64:67], v[176:179], v[212:215], v[64:67]
	s_setprio 0
	s_barrier
	s_mov_b32 m0, s39
	v_lshl_add_u64 v[216:217], v[216:217], 0, s[6:7]
	ds_read_b128 v[180:183], v143 offset:49152
	ds_read_b128 v[188:191], v143 offset:50176
	ds_read_b128 v[192:195], v143 offset:51200
	ds_read_b128 v[196:199], v143 offset:52224
	ds_read_b128 v[200:203], v143 offset:53248
	ds_read_b128 v[204:207], v143 offset:54272
	ds_read_b128 v[208:211], v143 offset:55296
	ds_read_b128 v[212:215], v143 offset:56320
	global_load_lds_dwordx4 v[216:217], off
	v_lshl_add_u64 v[216:217], v[218:219], 0, s[6:7]
	s_mov_b32 m0, s40
	s_add_u32 s28, s28, 0x40080
	global_load_lds_dwordx4 v[216:217], off
	s_addc_u32 s29, s29, 0
	s_mov_b32 m0, s43
	v_lshl_add_u64 v[216:217], v[220:221], 0, s[6:7]
	global_load_lds_dwordx4 v138, s[28:29]
	s_mov_b32 m0, s44
	s_nop 0
	global_load_lds_dwordx4 v132, s[28:29]
	s_waitcnt vmcnt(6)
	s_waitcnt lgkmcnt(0)
	s_barrier
	s_setprio 1
	s_waitcnt lgkmcnt(0)
	v_mfma_f32_16x16x32_bf16 v[60:63], v[144:147], v[180:183], v[60:63]
	v_mfma_f32_16x16x32_bf16 v[56:59], v[152:155], v[180:183], v[56:59]
	s_mov_b32 m0, s41
	v_mfma_f32_16x16x32_bf16 v[52:55], v[144:147], v[192:195], v[52:55]
	global_load_lds_dwordx4 v[216:217], off
	v_mfma_f32_16x16x32_bf16 v[48:51], v[152:155], v[192:195], v[48:51]
	v_mfma_f32_16x16x32_bf16 v[36:39], v[144:147], v[200:203], v[36:39]
	v_mfma_f32_16x16x32_bf16 v[32:35], v[152:155], v[200:203], v[32:35]
	v_mfma_f32_16x16x32_bf16 v[20:23], v[144:147], v[208:211], v[20:23]
	v_mfma_f32_16x16x32_bf16 v[16:19], v[152:155], v[208:211], v[16:19]
	v_mfma_f32_16x16x32_bf16 v[60:63], v[148:151], v[188:191], v[60:63]
	v_mfma_f32_16x16x32_bf16 v[56:59], v[156:159], v[188:191], v[56:59]
	v_mfma_f32_16x16x32_bf16 v[52:55], v[148:151], v[196:199], v[52:55]
	v_mfma_f32_16x16x32_bf16 v[48:51], v[156:159], v[196:199], v[48:51]
	v_mfma_f32_16x16x32_bf16 v[36:39], v[148:151], v[204:207], v[36:39]
	v_mfma_f32_16x16x32_bf16 v[32:35], v[156:159], v[204:207], v[32:35]
	v_mfma_f32_16x16x32_bf16 v[20:23], v[148:151], v[212:215], v[20:23]
	v_mfma_f32_16x16x32_bf16 v[16:19], v[156:159], v[212:215], v[16:19]
	v_lshl_add_u64 v[216:217], v[222:223], 0, s[6:7]
	s_mov_b32 m0, s42
	s_setprio 0
	s_setprio 1
	v_mfma_f32_16x16x32_bf16 v[44:47], v[164:167], v[180:183], v[44:47]
	global_load_lds_dwordx4 v[216:217], off
	v_mfma_f32_16x16x32_bf16 v[40:43], v[172:175], v[180:183], v[40:43]
	v_mfma_f32_16x16x32_bf16 v[28:31], v[164:167], v[192:195], v[28:31]
	v_mfma_f32_16x16x32_bf16 v[24:27], v[172:175], v[192:195], v[24:27]
	v_mfma_f32_16x16x32_bf16 v[12:15], v[164:167], v[200:203], v[12:15]
	v_mfma_f32_16x16x32_bf16 v[8:11], v[172:175], v[200:203], v[8:11]
	v_mfma_f32_16x16x32_bf16 v[4:7], v[164:167], v[208:211], v[4:7]
	v_mfma_f32_16x16x32_bf16 v[0:3], v[172:175], v[208:211], v[0:3]
	v_mfma_f32_16x16x32_bf16 v[44:47], v[168:171], v[188:191], v[44:47]
	s_add_i32 s54, s54, 2
	v_mfma_f32_16x16x32_bf16 v[40:43], v[176:179], v[188:191], v[40:43]
	s_add_u32 s26, s26, 0x100
	v_mfma_f32_16x16x32_bf16 v[28:31], v[168:171], v[196:199], v[28:31]
	s_addc_u32 s27, s27, 0
	v_mfma_f32_16x16x32_bf16 v[24:27], v[176:179], v[196:199], v[24:27]
	s_add_u32 s52, s52, 0x100
	v_mfma_f32_16x16x32_bf16 v[12:15], v[168:171], v[204:207], v[12:15]
	s_addc_u32 s53, s53, 0
	v_mfma_f32_16x16x32_bf16 v[8:11], v[176:179], v[204:207], v[8:11]
	s_cmp_gt_u32 s54, 13
	v_mfma_f32_16x16x32_bf16 v[4:7], v[168:171], v[212:215], v[4:7]
	v_mfma_f32_16x16x32_bf16 v[0:3], v[176:179], v[212:215], v[0:3]
	s_setprio 0
	s_barrier
	s_cbranch_scc0 .LBB0_993
	s_and_b64 vcc, exec, s[8:9]
	s_cbranch_vccz .LBB0_996
	s_barrier

.LBB0_1272:
	ds_read_b128 v[24:27], v182
	ds_read_b128 v[28:31], v182 offset:16
	ds_read_b128 v[16:19], v182 offset:2048
	ds_read_b128 v[20:23], v182 offset:2064
	ds_read_b128 v[8:11], v182 offset:16384
	ds_read_b128 v[12:15], v182 offset:16400
	ds_read_b128 v[0:3], v182 offset:18432
	ds_read_b128 v[4:7], v182 offset:18448
	s_add_u32 s30, s28, 0xfffe0080
	s_addc_u32 s31, s29, -1
	s_cmp_eq_u32 s65, 4
	s_cselect_b32 s35, s15, s31
	s_cselect_b32 s34, s57, s30
	s_cselect_b32 s31, s17, s64
	s_cselect_b32 s30, s62, s63
	s_add_i32 m0, s25, 0xc000
	ds_read_b128 v[172:175], v183
	ds_read_b128 v[176:179], v183 offset:16
	ds_read_b128 v[188:191], v183 offset:2048
	ds_read_b128 v[192:195], v183 offset:2064
	ds_read_b128 v[196:199], v183 offset:4096
	ds_read_b128 v[200:203], v183 offset:4112
	ds_read_b128 v[204:207], v183 offset:6144
	ds_read_b128 v[208:211], v183 offset:6160
	global_load_lds_dwordx4 v164, s[28:29]
	s_add_i32 m0, s25, 0xe000
	v_mov_b32_e32 v167, v165
	global_load_lds_dwordx4 v166, s[28:29]
	s_waitcnt vmcnt(8)
	s_waitcnt lgkmcnt(0)
	s_barrier
	s_setprio 1
	s_waitcnt lgkmcnt(0)
	v_mfma_f32_16x16x128_f8f6f4 v[156:159], v[24:31], v[172:179], v[156:159]
	v_mfma_f32_16x16x128_f8f6f4 v[148:151], v[16:23], v[172:179], v[148:151]
	v_mfma_f32_16x16x128_f8f6f4 v[140:143], v[24:31], v[188:195], v[140:143]
	v_mfma_f32_16x16x128_f8f6f4 v[132:135], v[16:23], v[188:195], v[132:135]
	v_mfma_f32_16x16x128_f8f6f4 v[124:127], v[24:31], v[196:203], v[124:127]
	v_mfma_f32_16x16x128_f8f6f4 v[116:119], v[16:23], v[196:203], v[116:119]
	v_mfma_f32_16x16x128_f8f6f4 v[108:111], v[24:31], v[204:211], v[108:111]
	v_mfma_f32_16x16x128_f8f6f4 v[100:103], v[16:23], v[204:211], v[100:103]
	s_setprio 0
	s_setprio 1
	v_mfma_f32_16x16x128_f8f6f4 v[152:155], v[8:15], v[172:179], v[152:155]
	v_mfma_f32_16x16x128_f8f6f4 v[144:147], v[0:7], v[172:179], v[144:147]
	v_mfma_f32_16x16x128_f8f6f4 v[136:139], v[8:15], v[188:195], v[136:139]
	v_mfma_f32_16x16x128_f8f6f4 v[128:131], v[0:7], v[188:195], v[128:131]
	v_mfma_f32_16x16x128_f8f6f4 v[120:123], v[8:15], v[196:203], v[120:123]
	v_mfma_f32_16x16x128_f8f6f4 v[112:115], v[0:7], v[196:203], v[112:115]
	v_mfma_f32_16x16x128_f8f6f4 v[104:107], v[8:15], v[204:211], v[104:107]
	v_mfma_f32_16x16x128_f8f6f4 v[96:99], v[0:7], v[204:211], v[96:99]
	s_setprio 0
	s_barrier
	s_mov_b32 m0, s27
	ds_read_b128 v[188:191], v183 offset:16384
	ds_read_b128 v[192:195], v183 offset:16400
	ds_read_b128 v[196:199], v183 offset:18432
	ds_read_b128 v[200:203], v183 offset:18448
	ds_read_b128 v[204:207], v183 offset:20480
	ds_read_b128 v[208:211], v183 offset:20496
	ds_read_b128 v[212:215], v183 offset:22528
	ds_read_b128 v[216:219], v183 offset:22544
	global_load_lds_dwordx4 v162, s[30:31]
	s_mov_b32 m0, s36
	s_add_u32 s66, s30, 0x20000
	global_load_lds_dwordx4 v168, s[30:31]
	s_addc_u32 s67, s31, 0
	s_mov_b32 m0, s37
	v_mov_b32_e32 v163, v165
	global_load_lds_dwordx4 v162, s[66:67]
	s_mov_b32 m0, s38
	v_mov_b32_e32 v169, v165
	global_load_lds_dwordx4 v168, s[66:67]
	s_waitcnt vmcnt(6)
	s_waitcnt lgkmcnt(0)
	s_barrier
	s_setprio 1
	s_waitcnt lgkmcnt(0)
	v_mfma_f32_16x16x128_f8f6f4 v[92:95], v[24:31], v[188:195], v[92:95]
	v_mfma_f32_16x16x128_f8f6f4 v[84:87], v[16:23], v[188:195], v[84:87]
	s_mov_b32 m0, s25
	v_lshl_add_u64 v[178:179], s[30:31], 0, v[162:163]
	v_mfma_f32_16x16x128_f8f6f4 v[76:79], v[24:31], v[196:203], v[76:79]
	global_load_lds_dwordx4 v164, s[34:35]
	v_mfma_f32_16x16x128_f8f6f4 v[68:71], v[16:23], v[196:203], v[68:71]
	v_mfma_f32_16x16x128_f8f6f4 v[60:63], v[24:31], v[204:211], v[60:63]
	v_mfma_f32_16x16x128_f8f6f4 v[52:55], v[16:23], v[204:211], v[52:55]
	v_mfma_f32_16x16x128_f8f6f4 v[44:47], v[24:31], v[212:219], v[44:47]
	v_mfma_f32_16x16x128_f8f6f4 v[36:39], v[16:23], v[212:219], v[36:39]
	s_mov_b32 m0, s39
	v_lshl_add_u64 v[176:177], s[30:31], 0, v[168:169]
	s_setprio 0
	s_setprio 1
	v_mfma_f32_16x16x128_f8f6f4 v[88:91], v[8:15], v[188:195], v[88:91]
	global_load_lds_dwordx4 v166, s[34:35]
	v_lshl_add_u64 v[174:175], s[34:35], 0, v[164:165]
	v_lshl_add_u64 v[172:173], s[34:35], 0, v[166:167]
	v_mfma_f32_16x16x128_f8f6f4 v[80:83], v[0:7], v[188:195], v[80:83]
	v_mfma_f32_16x16x128_f8f6f4 v[72:75], v[8:15], v[196:203], v[72:75]
	v_mfma_f32_16x16x128_f8f6f4 v[64:67], v[0:7], v[196:203], v[64:67]
	v_mfma_f32_16x16x128_f8f6f4 v[56:59], v[8:15], v[204:211], v[56:59]
	v_mfma_f32_16x16x128_f8f6f4 v[48:51], v[0:7], v[204:211], v[48:51]
	v_mfma_f32_16x16x128_f8f6f4 v[40:43], v[8:15], v[212:219], v[40:43]
	v_mfma_f32_16x16x128_f8f6f4 v[32:35], v[0:7], v[212:219], v[32:35]
	s_setprio 0
	s_barrier
	ds_read_b128 v[0:3], v182 offset:32768
	ds_read_b128 v[4:7], v182 offset:32784
	ds_read_b128 v[8:11], v182 offset:34816
	ds_read_b128 v[12:15], v182 offset:34832
	ds_read_b128 v[16:19], v182 offset:49152
	ds_read_b128 v[20:23], v182 offset:49168
	ds_read_b128 v[24:27], v182 offset:51200
	ds_read_b128 v[28:31], v182 offset:51216
	s_add_u32 s34, s34, 0x20000
	s_addc_u32 s35, s35, 0
	s_mov_b32 m0, s40
	ds_read_b128 v[188:191], v183 offset:32768
	ds_read_b128 v[192:195], v183 offset:32784
	ds_read_b128 v[196:199], v183 offset:34816
	ds_read_b128 v[200:203], v183 offset:34832
	ds_read_b128 v[204:207], v183 offset:36864
	ds_read_b128 v[208:211], v183 offset:36880
	ds_read_b128 v[212:215], v183 offset:38912
	ds_read_b128 v[216:219], v183 offset:38928
	global_load_lds_dwordx4 v164, s[34:35]
	s_mov_b32 m0, s41
	s_nop 0
	global_load_lds_dwordx4 v166, s[34:35]
	s_waitcnt vmcnt(8)
	s_waitcnt lgkmcnt(0)
	s_barrier
	s_setprio 1
	s_waitcnt lgkmcnt(0)
	v_mfma_f32_16x16x128_f8f6f4 v[156:159], v[0:7], v[188:195], v[156:159]
	v_mfma_f32_16x16x128_f8f6f4 v[148:151], v[8:15], v[188:195], v[148:151]
	v_mfma_f32_16x16x128_f8f6f4 v[140:143], v[0:7], v[196:203], v[140:143]
	v_mfma_f32_16x16x128_f8f6f4 v[132:135], v[8:15], v[196:203], v[132:135]
	v_mfma_f32_16x16x128_f8f6f4 v[124:127], v[0:7], v[204:211], v[124:127]
	v_mfma_f32_16x16x128_f8f6f4 v[116:119], v[8:15], v[204:211], v[116:119]
	v_mfma_f32_16x16x128_f8f6f4 v[108:111], v[0:7], v[212:219], v[108:111]
	v_mfma_f32_16x16x128_f8f6f4 v[100:103], v[8:15], v[212:219], v[100:103]
	s_setprio 0
	s_setprio 1
	v_mfma_f32_16x16x128_f8f6f4 v[152:155], v[16:23], v[188:195], v[152:155]
	v_mfma_f32_16x16x128_f8f6f4 v[144:147], v[24:31], v[188:195], v[144:147]
	v_mfma_f32_16x16x128_f8f6f4 v[136:139], v[16:23], v[196:203], v[136:139]
	v_mfma_f32_16x16x128_f8f6f4 v[128:131], v[24:31], v[196:203], v[128:131]
	v_mfma_f32_16x16x128_f8f6f4 v[120:123], v[16:23], v[204:211], v[120:123]
	v_mfma_f32_16x16x128_f8f6f4 v[112:115], v[24:31], v[204:211], v[112:115]
	v_mfma_f32_16x16x128_f8f6f4 v[104:107], v[16:23], v[212:219], v[104:107]
	v_mfma_f32_16x16x128_f8f6f4 v[96:99], v[24:31], v[212:219], v[96:99]
	s_setprio 0
	s_barrier
	s_mov_b32 m0, s43
	v_lshl_add_u64 v[178:179], v[178:179], 0, s[6:7]
	ds_read_b128 v[188:191], v183 offset:49152
	ds_read_b128 v[192:195], v183 offset:49168
	ds_read_b128 v[196:199], v183 offset:51200
	ds_read_b128 v[200:203], v183 offset:51216
	ds_read_b128 v[204:207], v183 offset:53248
	ds_read_b128 v[208:211], v183 offset:53264
	ds_read_b128 v[212:215], v183 offset:55296
	ds_read_b128 v[216:219], v183 offset:55312
	global_load_lds_dwordx4 v[178:179], off
	v_lshl_add_u64 v[176:177], v[176:177], 0, s[6:7]
	s_mov_b32 m0, s44
	s_add_u32 s30, s30, 0x20080
	global_load_lds_dwordx4 v[176:177], off
	s_addc_u32 s31, s31, 0
	s_mov_b32 m0, s48
	v_lshl_add_u64 v[174:175], v[174:175], 0, s[6:7]
	global_load_lds_dwordx4 v162, s[30:31]
	s_mov_b32 m0, s49
	v_lshl_add_u64 v[172:173], v[172:173], 0, s[6:7]
	global_load_lds_dwordx4 v168, s[30:31]
	s_waitcnt vmcnt(6)
	s_waitcnt lgkmcnt(0)
	s_barrier
	s_setprio 1
	s_waitcnt lgkmcnt(0)
	v_mfma_f32_16x16x128_f8f6f4 v[92:95], v[0:7], v[188:195], v[92:95]
	v_mfma_f32_16x16x128_f8f6f4 v[84:87], v[8:15], v[188:195], v[84:87]
	s_mov_b32 m0, s45
	v_mfma_f32_16x16x128_f8f6f4 v[76:79], v[0:7], v[196:203], v[76:79]
	global_load_lds_dwordx4 v[174:175], off
	v_mfma_f32_16x16x128_f8f6f4 v[68:71], v[8:15], v[196:203], v[68:71]
	v_mfma_f32_16x16x128_f8f6f4 v[60:63], v[0:7], v[204:211], v[60:63]
	v_mfma_f32_16x16x128_f8f6f4 v[52:55], v[8:15], v[204:211], v[52:55]
	v_mfma_f32_16x16x128_f8f6f4 v[44:47], v[0:7], v[212:219], v[44:47]
	v_mfma_f32_16x16x128_f8f6f4 v[36:39], v[8:15], v[212:219], v[36:39]
	s_mov_b32 m0, s47
	s_setprio 0
	s_setprio 1
	v_mfma_f32_16x16x128_f8f6f4 v[88:91], v[16:23], v[188:195], v[88:91]
	s_add_i32 s65, s65, 2
	global_load_lds_dwordx4 v[172:173], off
	v_mfma_f32_16x16x128_f8f6f4 v[80:83], v[24:31], v[188:195], v[80:83]
	s_add_u32 s28, s28, 0x100
	v_mfma_f32_16x16x128_f8f6f4 v[72:75], v[16:23], v[196:203], v[72:75]
	s_addc_u32 s29, s29, 0
	v_mfma_f32_16x16x128_f8f6f4 v[64:67], v[24:31], v[196:203], v[64:67]
	s_add_u32 s63, s63, 0x100
	v_mfma_f32_16x16x128_f8f6f4 v[56:59], v[16:23], v[204:211], v[56:59]
	s_addc_u32 s64, s64, 0
	v_mfma_f32_16x16x128_f8f6f4 v[48:51], v[24:31], v[204:211], v[48:51]
	s_cmp_gt_u32 s65, 5
	v_mfma_f32_16x16x128_f8f6f4 v[40:43], v[16:23], v[212:219], v[40:43]
	v_mfma_f32_16x16x128_f8f6f4 v[32:35], v[24:31], v[212:219], v[32:35]
	s_setprio 0
	s_barrier
	s_cbranch_scc0 .LBB0_1272
	s_nop 15
	s_nop 15
	s_and_b64 vcc, exec, s[8:9]
	s_cbranch_vccz .LBB0_1275
	s_barrier

.LBB0_1349:
	ds_read_b128 v[24:27], v181
	ds_read_b128 v[28:31], v181 offset:16
	ds_read_b128 v[16:19], v181 offset:2048
	ds_read_b128 v[20:23], v181 offset:2064
	ds_read_b128 v[8:11], v181 offset:16384
	ds_read_b128 v[12:15], v181 offset:16400
	ds_read_b128 v[0:3], v181 offset:18432
	ds_read_b128 v[4:7], v181 offset:18448
	s_add_u32 s34, s30, 0xfff90080
	s_addc_u32 s35, s31, -1
	s_cmp_eq_u32 s74, 24
	s_cselect_b32 s37, s1, s35
	s_cselect_b32 s36, s0, s34
	s_cselect_b32 s35, s27, s73
	s_cselect_b32 s34, s26, s72
	s_add_i32 m0, s29, 0xc000
	ds_read_b128 v[172:175], v182
	ds_read_b128 v[176:179], v182 offset:16
	ds_read_b128 v[188:191], v182 offset:2048
	ds_read_b128 v[192:195], v182 offset:2064
	ds_read_b128 v[196:199], v182 offset:4096
	ds_read_b128 v[200:203], v182 offset:4112
	ds_read_b128 v[204:207], v182 offset:6144
	ds_read_b128 v[208:211], v182 offset:6160
	global_load_lds_dwordx4 v162, s[30:31]
	s_add_i32 m0, s29, 0xe000
	v_mov_b32_e32 v167, v163
	global_load_lds_dwordx4 v166, s[30:31]
	s_waitcnt vmcnt(8)
	s_waitcnt lgkmcnt(0)
	s_barrier
	s_setprio 1
	s_waitcnt lgkmcnt(0)
	v_mfma_f32_16x16x128_f8f6f4 v[156:159], v[24:31], v[172:179], v[156:159]
	v_mfma_f32_16x16x128_f8f6f4 v[152:155], v[16:23], v[172:179], v[152:155]
	v_mfma_f32_16x16x128_f8f6f4 v[148:151], v[24:31], v[188:195], v[148:151]
	v_mfma_f32_16x16x128_f8f6f4 v[140:143], v[16:23], v[188:195], v[140:143]
	v_mfma_f32_16x16x128_f8f6f4 v[132:135], v[24:31], v[196:203], v[132:135]
	v_mfma_f32_16x16x128_f8f6f4 v[124:127], v[16:23], v[196:203], v[124:127]
	v_mfma_f32_16x16x128_f8f6f4 v[116:119], v[24:31], v[204:211], v[116:119]
	v_mfma_f32_16x16x128_f8f6f4 v[108:111], v[16:23], v[204:211], v[108:111]
	s_setprio 0
	s_setprio 1
	v_mfma_f32_16x16x128_f8f6f4 v[144:147], v[8:15], v[172:179], v[144:147]
	v_mfma_f32_16x16x128_f8f6f4 v[136:139], v[0:7], v[172:179], v[136:139]
	v_mfma_f32_16x16x128_f8f6f4 v[128:131], v[8:15], v[188:195], v[128:131]
	v_mfma_f32_16x16x128_f8f6f4 v[120:123], v[0:7], v[188:195], v[120:123]
	v_mfma_f32_16x16x128_f8f6f4 v[112:115], v[8:15], v[196:203], v[112:115]
	v_mfma_f32_16x16x128_f8f6f4 v[104:107], v[0:7], v[196:203], v[104:107]
	v_mfma_f32_16x16x128_f8f6f4 v[100:103], v[8:15], v[204:211], v[100:103]
	v_mfma_f32_16x16x128_f8f6f4 v[96:99], v[0:7], v[204:211], v[96:99]
	s_setprio 0
	s_barrier
	s_mov_b32 m0, s39
	ds_read_b128 v[188:191], v182 offset:16384
	ds_read_b128 v[192:195], v182 offset:16400
	ds_read_b128 v[196:199], v182 offset:18432
	ds_read_b128 v[200:203], v182 offset:18448
	ds_read_b128 v[204:207], v182 offset:20480
	ds_read_b128 v[208:211], v182 offset:20496
	ds_read_b128 v[212:215], v182 offset:22528
	ds_read_b128 v[216:219], v182 offset:22544
	global_load_lds_dwordx4 v164, s[34:35]
	s_mov_b32 m0, s40
	s_add_u32 s76, s34, 0x70000
	global_load_lds_dwordx4 v168, s[34:35]
	s_addc_u32 s77, s35, 0
	s_mov_b32 m0, s41
	v_mov_b32_e32 v165, v163
	global_load_lds_dwordx4 v164, s[76:77]
	s_mov_b32 m0, s42
	v_mov_b32_e32 v169, v163
	global_load_lds_dwordx4 v168, s[76:77]
	s_waitcnt vmcnt(6)
	s_waitcnt lgkmcnt(0)
	s_barrier
	s_setprio 1
	s_waitcnt lgkmcnt(0)
	v_mfma_f32_16x16x128_f8f6f4 v[92:95], v[24:31], v[188:195], v[92:95]
	v_mfma_f32_16x16x128_f8f6f4 v[88:91], v[16:23], v[188:195], v[88:91]
	s_mov_b32 m0, s29
	v_lshl_add_u64 v[178:179], s[34:35], 0, v[164:165]
	v_mfma_f32_16x16x128_f8f6f4 v[84:87], v[24:31], v[196:203], v[84:87]
	global_load_lds_dwordx4 v162, s[36:37]
	v_mfma_f32_16x16x128_f8f6f4 v[76:79], v[16:23], v[196:203], v[76:79]
	v_mfma_f32_16x16x128_f8f6f4 v[68:71], v[24:31], v[204:211], v[68:71]
	v_mfma_f32_16x16x128_f8f6f4 v[60:63], v[16:23], v[204:211], v[60:63]
	v_mfma_f32_16x16x128_f8f6f4 v[52:55], v[24:31], v[212:219], v[52:55]
	v_mfma_f32_16x16x128_f8f6f4 v[44:47], v[16:23], v[212:219], v[44:47]
	s_mov_b32 m0, s43
	v_lshl_add_u64 v[176:177], s[34:35], 0, v[168:169]
	s_setprio 0
	s_setprio 1
	v_mfma_f32_16x16x128_f8f6f4 v[80:83], v[8:15], v[188:195], v[80:83]
	global_load_lds_dwordx4 v166, s[36:37]
	v_lshl_add_u64 v[174:175], s[36:37], 0, v[162:163]
	v_lshl_add_u64 v[172:173], s[36:37], 0, v[166:167]
	v_mfma_f32_16x16x128_f8f6f4 v[72:75], v[0:7], v[188:195], v[72:75]
	v_mfma_f32_16x16x128_f8f6f4 v[64:67], v[8:15], v[196:203], v[64:67]
	v_mfma_f32_16x16x128_f8f6f4 v[56:59], v[0:7], v[196:203], v[56:59]
	v_mfma_f32_16x16x128_f8f6f4 v[48:51], v[8:15], v[204:211], v[48:51]
	v_mfma_f32_16x16x128_f8f6f4 v[40:43], v[0:7], v[204:211], v[40:43]
	v_mfma_f32_16x16x128_f8f6f4 v[36:39], v[8:15], v[212:219], v[36:39]
	v_mfma_f32_16x16x128_f8f6f4 v[32:35], v[0:7], v[212:219], v[32:35]
	s_setprio 0
	s_barrier
	ds_read_b128 v[0:3], v181 offset:32768
	ds_read_b128 v[4:7], v181 offset:32784
	ds_read_b128 v[8:11], v181 offset:34816
	ds_read_b128 v[12:15], v181 offset:34832
	ds_read_b128 v[16:19], v181 offset:49152
	ds_read_b128 v[20:23], v181 offset:49168
	ds_read_b128 v[24:27], v181 offset:51200
	ds_read_b128 v[28:31], v181 offset:51216
	s_add_u32 s36, s36, 0x70000
	s_addc_u32 s37, s37, 0
	s_mov_b32 m0, s44
	ds_read_b128 v[188:191], v182 offset:32768
	ds_read_b128 v[192:195], v182 offset:32784
	ds_read_b128 v[196:199], v182 offset:34816
	ds_read_b128 v[200:203], v182 offset:34832
	ds_read_b128 v[204:207], v182 offset:36864
	ds_read_b128 v[208:211], v182 offset:36880
	ds_read_b128 v[212:215], v182 offset:38912
	ds_read_b128 v[216:219], v182 offset:38928
	global_load_lds_dwordx4 v162, s[36:37]
	s_mov_b32 m0, s45
	s_nop 0
	global_load_lds_dwordx4 v166, s[36:37]
	s_waitcnt vmcnt(8)
	s_waitcnt lgkmcnt(0)
	s_barrier
	s_setprio 1
	s_waitcnt lgkmcnt(0)
	v_mfma_f32_16x16x128_f8f6f4 v[156:159], v[0:7], v[188:195], v[156:159]
	v_mfma_f32_16x16x128_f8f6f4 v[152:155], v[8:15], v[188:195], v[152:155]
	v_mfma_f32_16x16x128_f8f6f4 v[148:151], v[0:7], v[196:203], v[148:151]
	v_mfma_f32_16x16x128_f8f6f4 v[140:143], v[8:15], v[196:203], v[140:143]
	v_mfma_f32_16x16x128_f8f6f4 v[132:135], v[0:7], v[204:211], v[132:135]
	v_mfma_f32_16x16x128_f8f6f4 v[124:127], v[8:15], v[204:211], v[124:127]
	v_mfma_f32_16x16x128_f8f6f4 v[116:119], v[0:7], v[212:219], v[116:119]
	v_mfma_f32_16x16x128_f8f6f4 v[108:111], v[8:15], v[212:219], v[108:111]
	s_setprio 0
	s_setprio 1
	v_mfma_f32_16x16x128_f8f6f4 v[144:147], v[16:23], v[188:195], v[144:147]
	v_mfma_f32_16x16x128_f8f6f4 v[136:139], v[24:31], v[188:195], v[136:139]
	v_mfma_f32_16x16x128_f8f6f4 v[128:131], v[16:23], v[196:203], v[128:131]
	v_mfma_f32_16x16x128_f8f6f4 v[120:123], v[24:31], v[196:203], v[120:123]
	v_mfma_f32_16x16x128_f8f6f4 v[112:115], v[16:23], v[204:211], v[112:115]
	v_mfma_f32_16x16x128_f8f6f4 v[104:107], v[24:31], v[204:211], v[104:107]
	v_mfma_f32_16x16x128_f8f6f4 v[100:103], v[16:23], v[212:219], v[100:103]
	v_mfma_f32_16x16x128_f8f6f4 v[96:99], v[24:31], v[212:219], v[96:99]
	s_setprio 0
	s_barrier
	s_mov_b32 m0, s48
	v_lshl_add_u64 v[178:179], v[178:179], 0, s[8:9]
	ds_read_b128 v[188:191], v182 offset:49152
	ds_read_b128 v[192:195], v182 offset:49168
	ds_read_b128 v[196:199], v182 offset:51200
	ds_read_b128 v[200:203], v182 offset:51216
	ds_read_b128 v[204:207], v182 offset:53248
	ds_read_b128 v[208:211], v182 offset:53264
	ds_read_b128 v[212:215], v182 offset:55296
	ds_read_b128 v[216:219], v182 offset:55312
	global_load_lds_dwordx4 v[178:179], off
	v_lshl_add_u64 v[176:177], v[176:177], 0, s[8:9]
	s_mov_b32 m0, s49
	s_add_u32 s34, s34, 0x70080
	global_load_lds_dwordx4 v[176:177], off
	s_addc_u32 s35, s35, 0
	s_mov_b32 m0, s57
	v_lshl_add_u64 v[174:175], v[174:175], 0, s[8:9]
	global_load_lds_dwordx4 v164, s[34:35]
	s_mov_b32 m0, s62
	v_lshl_add_u64 v[172:173], v[172:173], 0, s[8:9]
	global_load_lds_dwordx4 v168, s[34:35]
	s_waitcnt vmcnt(6)
	s_waitcnt lgkmcnt(0)
	s_barrier
	s_setprio 1
	s_waitcnt lgkmcnt(0)
	v_mfma_f32_16x16x128_f8f6f4 v[92:95], v[0:7], v[188:195], v[92:95]
	v_mfma_f32_16x16x128_f8f6f4 v[88:91], v[8:15], v[188:195], v[88:91]
	s_mov_b32 m0, s52
	v_mfma_f32_16x16x128_f8f6f4 v[84:87], v[0:7], v[196:203], v[84:87]
	global_load_lds_dwordx4 v[174:175], off
	v_mfma_f32_16x16x128_f8f6f4 v[76:79], v[8:15], v[196:203], v[76:79]
	v_mfma_f32_16x16x128_f8f6f4 v[68:71], v[0:7], v[204:211], v[68:71]
	v_mfma_f32_16x16x128_f8f6f4 v[60:63], v[8:15], v[204:211], v[60:63]
	v_mfma_f32_16x16x128_f8f6f4 v[52:55], v[0:7], v[212:219], v[52:55]
	v_mfma_f32_16x16x128_f8f6f4 v[44:47], v[8:15], v[212:219], v[44:47]
	s_mov_b32 m0, s53
	s_setprio 0
	s_setprio 1
	v_mfma_f32_16x16x128_f8f6f4 v[80:83], v[16:23], v[188:195], v[80:83]
	s_add_i32 s74, s74, 2
	global_load_lds_dwordx4 v[172:173], off
	v_mfma_f32_16x16x128_f8f6f4 v[72:75], v[24:31], v[188:195], v[72:75]
	s_add_u32 s30, s30, 0x100
	v_mfma_f32_16x16x128_f8f6f4 v[64:67], v[16:23], v[196:203], v[64:67]
	s_addc_u32 s31, s31, 0
	v_mfma_f32_16x16x128_f8f6f4 v[56:59], v[24:31], v[196:203], v[56:59]
	s_add_u32 s72, s72, 0x100
	v_mfma_f32_16x16x128_f8f6f4 v[48:51], v[16:23], v[204:211], v[48:51]
	s_addc_u32 s73, s73, 0
	v_mfma_f32_16x16x128_f8f6f4 v[40:43], v[24:31], v[204:211], v[40:43]
	s_cmp_gt_u32 s74, 25
	v_mfma_f32_16x16x128_f8f6f4 v[36:39], v[16:23], v[212:219], v[36:39]
	v_mfma_f32_16x16x128_f8f6f4 v[32:35], v[24:31], v[212:219], v[32:35]
	s_setprio 0
	s_barrier
	s_cbranch_scc0 .LBB0_1349
	s_nop 15
	s_nop 15
	s_and_b64 vcc, exec, s[10:11]
	s_cbranch_vccz .LBB0_1352
	s_barrier
